# plus: LDS-DMA stage loads in the six GEMM K-loops use SGPR base + 32-bit VGPR offset instead of per-load 64-bit VALU address adds
# speedup vs baseline: 1.0091x; 1.0048x over previous
; #define PG8_STAGE(bufoff, gbase, voff) do { _Pragma("unroll") for (int _i = 0; _i < 2; ++_i) \
;         __builtin_amdgcn_global_load_lds((const unsigned*)((const char*)(gbase) + (voff)[_i]), (LAS unsigned*)(lds + (bufoff) + ldsw + _i * 8192), 16, 0, 0); } while (0)
; #define PG8_LDA(dst, b, h) do { _Pragma("unroll") for (int m = 0; m < 4; ++m) _Pragma("unroll") for (int k = 0; k < 2; ++k) dst[m][k] = *(const LAS bf16x8*)(lds + PG8_SA(b, h) + aoff + m * 2048 + k * 1024); } while (0)
; #define PG8_LDB(dst, b, h) do { _Pragma("unroll") for (int n = 0; n < 2; ++n) _Pragma("unroll") for (int k = 0; k < 2; ++k) dst[n][k] = *(const LAS bf16x8*)(lds + PG8_SB(b, h) + boff + n * 2048 + k * 1024); } while (0)
; #define PG8_MMA(ai, bj, At, Bt) do { __builtin_amdgcn_s_setprio(1); _Pragma("unroll") for (int m = 0; m < 4; ++m) _Pragma("unroll") for (int n = 0; n < 2; ++n) _Pragma("unroll") for (int k = 0; k < 2; ++k) \
;         acc[ai][bj][m][n] = __builtin_amdgcn_mfma_f32_16x16x32_bf16(Bt[n][k], At[m][k], acc[ai][bj][m][n], 0, 0, 0); __builtin_amdgcn_s_setprio(0); } while (0)
; #define PG8_WAIT_V(n) asm volatile("s_waitcnt vmcnt(" #n ")" ::: "memory")
; #define PG8_WAIT_L(n) asm volatile("s_waitcnt lgkmcnt(" #n ")" ::: "memory")
; #define PG8_BAR __builtin_amdgcn_s_barrier()
; #define PG8_SCHED __builtin_amdgcn_sched_barrier(0)
; template <class Epi, class Sched, bool ALIGN_EPI = false, bool SP2 = false>
; __device__ __forceinline__ void gemm_phase(LAS unsigned char* lds, const Gemm g, const Sched& S, const Epi& E, const int tid_) {
;     ...
;             if constexpr (SP2) {
;             PG8_LDB(B0, 0, 0); PG8_LDB(B1, 0, 1); PG8_SCHED; PG8_LDA(At, 0, 0); PG8_STAGE(PG8_SA(1, 1), a1 + hstep, voffA);
;             PG8_WAIT_V(8); PG8_WAIT_L(0); PG8_BAR; PG8_MMA(0, 0, At, B0); PG8_MMA(0, 1, At, B1); PG8_BAR; PG8_SCHED;
;             PG8_LDA(At, 0, 1); PG8_STAGE(PG8_SB(0, 0), b2, voffB); PG8_STAGE(PG8_SB(0, 1), b2 + hstep, voffB); PG8_STAGE(PG8_SA(0, 0), a2, voffA);
;             PG8_WAIT_V(8); PG8_WAIT_L(0); PG8_BAR; PG8_MMA(1, 0, At, B0); PG8_MMA(1, 1, At, B1); PG8_BAR; PG8_SCHED;
.LBB0_34:
	s_add_u32 s48, s46, 0xfff80080
	s_addc_u32 s49, s47, -1
	s_add_i32 s68, 0, 0x10000
	s_cmp_eq_u32 s67, 28
	s_cselect_b32 s51, s17, s49
	s_cselect_b32 s50, s21, s48
	v_add_u32_e32 v140, s68, v143
	s_cselect_b32 s49, s15, s66
	s_cselect_b32 s48, s64, s65
	s_add_i32 s70, 0, 0x14000
	s_nop 0
	ds_read_b128 v[146:149], v140
	ds_read_b128 v[150:153], v140 offset:1024
	ds_read_b128 v[154:157], v140 offset:2048
	ds_read_b128 v[158:161], v140 offset:3072
	v_add_u32_e32 v140, s70, v143
	ds_read_b128 v[162:165], v140
	ds_read_b128 v[166:169], v140 offset:1024
	ds_read_b128 v[170:173], v140 offset:2048
	ds_read_b128 v[174:177], v140 offset:3072
	s_add_i32 m0, s45, 0xc000
	ds_read_b128 v[178:181], v145
	ds_read_b128 v[182:185], v145 offset:1024
	ds_read_b128 v[200:203], v145 offset:2048
	ds_read_b128 v[204:207], v145 offset:3072
	ds_read_b128 v[208:211], v145 offset:4096
	ds_read_b128 v[212:215], v145 offset:5120
	ds_read_b128 v[216:219], v145 offset:6144
	ds_read_b128 v[220:223], v145 offset:7168
	global_load_lds_dwordx4 v136, s[46:47]
	s_add_i32 m0, s45, 0xe000
	s_nop 0
	global_load_lds_dwordx4 v138, s[46:47]
	s_waitcnt vmcnt(8)
	s_waitcnt lgkmcnt(0)
	s_barrier
	s_setprio 1
	s_waitcnt lgkmcnt(0)
	v_mfma_f32_16x16x32_bf16 v[126:129], v[146:149], v[178:181], v[126:129]
	v_mfma_f32_16x16x32_bf16 v[122:125], v[154:157], v[178:181], v[122:125]
	v_mfma_f32_16x16x32_bf16 v[110:113], v[146:149], v[200:203], v[110:113]
	v_mfma_f32_16x16x32_bf16 v[106:109], v[154:157], v[200:203], v[106:109]
	v_mfma_f32_16x16x32_bf16 v[94:97], v[146:149], v[208:211], v[94:97]
	v_mfma_f32_16x16x32_bf16 v[90:93], v[154:157], v[208:211], v[90:93]
	v_mfma_f32_16x16x32_bf16 v[78:81], v[146:149], v[216:219], v[78:81]
	v_mfma_f32_16x16x32_bf16 v[74:77], v[154:157], v[216:219], v[74:77]
	v_mfma_f32_16x16x32_bf16 v[126:129], v[150:153], v[182:185], v[126:129]
	v_mfma_f32_16x16x32_bf16 v[122:125], v[158:161], v[182:185], v[122:125]
	v_mfma_f32_16x16x32_bf16 v[110:113], v[150:153], v[204:207], v[110:113]
	v_mfma_f32_16x16x32_bf16 v[106:109], v[158:161], v[204:207], v[106:109]
	v_mfma_f32_16x16x32_bf16 v[94:97], v[150:153], v[212:215], v[94:97]
	v_mfma_f32_16x16x32_bf16 v[90:93], v[158:161], v[212:215], v[90:93]
	v_mfma_f32_16x16x32_bf16 v[78:81], v[150:153], v[220:223], v[78:81]
	v_mfma_f32_16x16x32_bf16 v[74:77], v[158:161], v[220:223], v[74:77]
	s_setprio 0
	s_setprio 1
	v_mfma_f32_16x16x32_bf16 v[118:121], v[162:165], v[178:181], v[118:121]
	v_mfma_f32_16x16x32_bf16 v[114:117], v[170:173], v[178:181], v[114:117]
	v_mfma_f32_16x16x32_bf16 v[102:105], v[162:165], v[200:203], v[102:105]
	v_mfma_f32_16x16x32_bf16 v[98:101], v[170:173], v[200:203], v[98:101]
	v_mfma_f32_16x16x32_bf16 v[86:89], v[162:165], v[208:211], v[86:89]
	v_mfma_f32_16x16x32_bf16 v[82:85], v[170:173], v[208:211], v[82:85]
	v_mfma_f32_16x16x32_bf16 v[70:73], v[162:165], v[216:219], v[70:73]
	v_mfma_f32_16x16x32_bf16 v[66:69], v[170:173], v[216:219], v[66:69]
	v_mfma_f32_16x16x32_bf16 v[118:121], v[166:169], v[182:185], v[118:121]
	v_mfma_f32_16x16x32_bf16 v[114:117], v[174:177], v[182:185], v[114:117]
	v_mfma_f32_16x16x32_bf16 v[102:105], v[166:169], v[204:207], v[102:105]
	v_mfma_f32_16x16x32_bf16 v[98:101], v[174:177], v[204:207], v[98:101]
	v_mfma_f32_16x16x32_bf16 v[86:89], v[166:169], v[212:215], v[86:89]
	v_mfma_f32_16x16x32_bf16 v[82:85], v[174:177], v[212:215], v[82:85]
	v_mfma_f32_16x16x32_bf16 v[70:73], v[166:169], v[220:223], v[70:73]
	v_mfma_f32_16x16x32_bf16 v[66:69], v[174:177], v[220:223], v[66:69]
	s_setprio 0
	s_barrier
	s_add_i32 s68, s68, s55
	s_mov_b32 m0, s68
	ds_read_b128 v[178:181], v145 offset:16384
	ds_read_b128 v[182:185], v145 offset:17408
	ds_read_b128 v[200:203], v145 offset:18432
	ds_read_b128 v[204:207], v145 offset:19456
	ds_read_b128 v[208:211], v145 offset:20480
	ds_read_b128 v[212:215], v145 offset:21504
	ds_read_b128 v[216:219], v145 offset:22528
	ds_read_b128 v[220:223], v145 offset:23552
	global_load_lds_dwordx4 v0, s[48:49]
	s_add_i32 m0, s68, 0x2000
	s_add_u32 s68, s48, 0x80000
	v_lshl_add_u64 v[192:193], s[48:49], 0, v[134:135]
	s_addc_u32 s69, s49, 0
	s_add_i32 s70, s70, s55
	global_load_lds_dwordx4 v134, s[48:49]
	s_mov_b32 m0, s70
	v_lshl_add_u64 v[236:237], s[50:51], 0, v[132:133]
	global_load_lds_dwordx4 v0, s[68:69]
	s_add_i32 m0, s70, 0x2000
	s_nop 0
	global_load_lds_dwordx4 v134, s[68:69]
	v_lshl_add_u64 v[224:225], s[50:51], 0, v[130:131]
	s_mov_b32 m0, s45
	s_nop 0
	global_load_lds_dwordx4 v130, s[50:51]
	s_mov_b32 m0, s56
	s_nop 0
	global_load_lds_dwordx4 v132, s[50:51]
	s_waitcnt vmcnt(8)
	s_waitcnt lgkmcnt(0)
	s_barrier
; #define PG8_STAGE(bufoff, gbase, voff) do { _Pragma("unroll") for (int _i = 0; _i < 2; ++_i) \
;         __builtin_amdgcn_global_load_lds((const unsigned*)((const char*)(gbase) + (voff)[_i]), (LAS unsigned*)(lds + (bufoff) + ldsw + _i * 8192), 16, 0, 0); } while (0)
; #define PG8_LDA(dst, b, h) do { _Pragma("unroll") for (int m = 0; m < 4; ++m) _Pragma("unroll") for (int k = 0; k < 2; ++k) dst[m][k] = *(const LAS bf16x8*)(lds + PG8_SA(b, h) + aoff + m * 2048 + k * 1024); } while (0)
; #define PG8_LDB(dst, b, h) do { _Pragma("unroll") for (int n = 0; n < 2; ++n) _Pragma("unroll") for (int k = 0; k < 2; ++k) dst[n][k] = *(const LAS bf16x8*)(lds + PG8_SB(b, h) + boff + n * 2048 + k * 1024); } while (0)
; #define PG8_MMA(ai, bj, At, Bt) do { __builtin_amdgcn_s_setprio(1); _Pragma("unroll") for (int m = 0; m < 4; ++m) _Pragma("unroll") for (int n = 0; n < 2; ++n) _Pragma("unroll") for (int k = 0; k < 2; ++k) \
;         acc[ai][bj][m][n] = __builtin_amdgcn_mfma_f32_16x16x32_bf16(Bt[n][k], At[m][k], acc[ai][bj][m][n], 0, 0, 0); __builtin_amdgcn_s_setprio(0); } while (0)
; #define PG8_WAIT_V(n) asm volatile("s_waitcnt vmcnt(" #n ")" ::: "memory")
; #define PG8_WAIT_L(n) asm volatile("s_waitcnt lgkmcnt(" #n ")" ::: "memory")
; #define PG8_BAR __builtin_amdgcn_s_barrier()
; #define PG8_SCHED __builtin_amdgcn_sched_barrier(0)
; template <class Epi, class Sched, bool ALIGN_EPI = false, bool SP2 = false>
; __device__ __forceinline__ void gemm_phase(LAS unsigned char* lds, const Gemm g, const Sched& S, const Epi& E, const int tid_) {
;     ...
;             PG8_WAIT_V(8); PG8_WAIT_L(0); PG8_BAR; PG8_MMA(1, 0, At, B0); PG8_MMA(1, 1, At, B1); PG8_BAR; PG8_SCHED;
;             PG8_LDB(B0, 1, 0); PG8_LDB(B1, 1, 1); PG8_SCHED; PG8_LDA(At, 1, 0); PG8_STAGE(PG8_SA(0, 1), a2 + hstep, voffA);
;             PG8_WAIT_V(8); PG8_WAIT_L(0); PG8_BAR; PG8_MMA(0, 0, At, B0); PG8_MMA(0, 1, At, B1); PG8_BAR; PG8_SCHED;
	s_setprio 1
	s_waitcnt lgkmcnt(0)
	v_mfma_f32_16x16x32_bf16 v[62:65], v[146:149], v[178:181], v[62:65]
	v_mfma_f32_16x16x32_bf16 v[58:61], v[154:157], v[178:181], v[58:61]
	v_mfma_f32_16x16x32_bf16 v[46:49], v[146:149], v[200:203], v[46:49]
	v_mfma_f32_16x16x32_bf16 v[42:45], v[154:157], v[200:203], v[42:45]
	v_mfma_f32_16x16x32_bf16 v[30:33], v[146:149], v[208:211], v[30:33]
	v_mfma_f32_16x16x32_bf16 v[26:29], v[154:157], v[208:211], v[26:29]
	v_mfma_f32_16x16x32_bf16 v[14:17], v[146:149], v[216:219], v[14:17]
	v_mfma_f32_16x16x32_bf16 v[10:13], v[154:157], v[216:219], v[10:13]
	v_mfma_f32_16x16x32_bf16 v[62:65], v[150:153], v[182:185], v[62:65]
	v_mfma_f32_16x16x32_bf16 v[58:61], v[158:161], v[182:185], v[58:61]
	v_mfma_f32_16x16x32_bf16 v[46:49], v[150:153], v[204:207], v[46:49]
	v_mfma_f32_16x16x32_bf16 v[42:45], v[158:161], v[204:207], v[42:45]
	v_mfma_f32_16x16x32_bf16 v[30:33], v[150:153], v[212:215], v[30:33]
	v_mfma_f32_16x16x32_bf16 v[26:29], v[158:161], v[212:215], v[26:29]
	v_mfma_f32_16x16x32_bf16 v[14:17], v[150:153], v[220:223], v[14:17]
	v_mfma_f32_16x16x32_bf16 v[10:13], v[158:161], v[220:223], v[10:13]
	s_setprio 0
	s_setprio 1
	v_mfma_f32_16x16x32_bf16 v[54:57], v[162:165], v[178:181], v[54:57]
	v_mfma_f32_16x16x32_bf16 v[50:53], v[170:173], v[178:181], v[50:53]
	v_mfma_f32_16x16x32_bf16 v[38:41], v[162:165], v[200:203], v[38:41]
	v_mfma_f32_16x16x32_bf16 v[34:37], v[170:173], v[200:203], v[34:37]
	v_mfma_f32_16x16x32_bf16 v[22:25], v[162:165], v[208:211], v[22:25]
	v_mfma_f32_16x16x32_bf16 v[18:21], v[170:173], v[208:211], v[18:21]
	v_mfma_f32_16x16x32_bf16 v[6:9], v[162:165], v[216:219], v[6:9]
	v_mfma_f32_16x16x32_bf16 v[2:5], v[170:173], v[216:219], v[2:5]
	v_mfma_f32_16x16x32_bf16 v[54:57], v[166:169], v[182:185], v[54:57]
	v_mfma_f32_16x16x32_bf16 v[50:53], v[174:177], v[182:185], v[50:53]
	v_mfma_f32_16x16x32_bf16 v[38:41], v[166:169], v[204:207], v[38:41]
	v_mfma_f32_16x16x32_bf16 v[34:37], v[174:177], v[204:207], v[34:37]
	v_mfma_f32_16x16x32_bf16 v[22:25], v[166:169], v[212:215], v[22:25]
	v_mfma_f32_16x16x32_bf16 v[18:21], v[174:177], v[212:215], v[18:21]
	v_mfma_f32_16x16x32_bf16 v[6:9], v[166:169], v[220:223], v[6:9]
	v_mfma_f32_16x16x32_bf16 v[2:5], v[174:177], v[220:223], v[2:5]
	s_setprio 0
	s_barrier
	s_add_i32 s68, 0, 0x18000
	s_add_i32 s69, 0, 0x1c000
	v_add_u32_e32 v158, s68, v143
	v_add_u32_e32 v174, s69, v143
	ds_read_b128 v[146:149], v158
	ds_read_b128 v[150:153], v158 offset:1024
	ds_read_b128 v[154:157], v158 offset:2048
	ds_read_b128 v[158:161], v158 offset:3072
	ds_read_b128 v[162:165], v174
	ds_read_b128 v[166:169], v174 offset:1024
	ds_read_b128 v[170:173], v174 offset:2048
	ds_read_b128 v[174:177], v174 offset:3072
	s_add_u32 s50, s50, 0x80000
	s_addc_u32 s51, s51, 0
	s_mov_b32 m0, s57
	ds_read_b128 v[178:181], v145 offset:32768
	ds_read_b128 v[182:185], v145 offset:33792
	ds_read_b128 v[200:203], v145 offset:34816
	ds_read_b128 v[204:207], v145 offset:35840
	ds_read_b128 v[208:211], v145 offset:36864
	ds_read_b128 v[212:215], v145 offset:37888
	ds_read_b128 v[216:219], v145 offset:38912
	ds_read_b128 v[220:223], v145 offset:39936
	global_load_lds_dwordx4 v130, s[50:51]
	s_mov_b32 m0, s58
	s_nop 0
	global_load_lds_dwordx4 v132, s[50:51]
	s_waitcnt vmcnt(8)
	s_waitcnt lgkmcnt(0)
	s_barrier
	s_setprio 1
	s_waitcnt lgkmcnt(0)
	v_mfma_f32_16x16x32_bf16 v[126:129], v[146:149], v[178:181], v[126:129]
	v_mfma_f32_16x16x32_bf16 v[122:125], v[154:157], v[178:181], v[122:125]
	v_mfma_f32_16x16x32_bf16 v[110:113], v[146:149], v[200:203], v[110:113]
	v_mfma_f32_16x16x32_bf16 v[106:109], v[154:157], v[200:203], v[106:109]
	v_mfma_f32_16x16x32_bf16 v[94:97], v[146:149], v[208:211], v[94:97]
	v_mfma_f32_16x16x32_bf16 v[90:93], v[154:157], v[208:211], v[90:93]
	v_mfma_f32_16x16x32_bf16 v[78:81], v[146:149], v[216:219], v[78:81]
	v_mfma_f32_16x16x32_bf16 v[74:77], v[154:157], v[216:219], v[74:77]
	v_mfma_f32_16x16x32_bf16 v[126:129], v[150:153], v[182:185], v[126:129]
	v_mfma_f32_16x16x32_bf16 v[122:125], v[158:161], v[182:185], v[122:125]
	v_mfma_f32_16x16x32_bf16 v[110:113], v[150:153], v[204:207], v[110:113]
	v_mfma_f32_16x16x32_bf16 v[106:109], v[158:161], v[204:207], v[106:109]
	v_mfma_f32_16x16x32_bf16 v[94:97], v[150:153], v[212:215], v[94:97]
	v_mfma_f32_16x16x32_bf16 v[90:93], v[158:161], v[212:215], v[90:93]
	v_mfma_f32_16x16x32_bf16 v[78:81], v[150:153], v[220:223], v[78:81]
	v_mfma_f32_16x16x32_bf16 v[74:77], v[158:161], v[220:223], v[74:77]
	s_setprio 0
	s_setprio 1
	v_mfma_f32_16x16x32_bf16 v[118:121], v[162:165], v[178:181], v[118:121]
	v_mfma_f32_16x16x32_bf16 v[114:117], v[170:173], v[178:181], v[114:117]
	v_mfma_f32_16x16x32_bf16 v[102:105], v[162:165], v[200:203], v[102:105]
	v_mfma_f32_16x16x32_bf16 v[98:101], v[170:173], v[200:203], v[98:101]
	v_mfma_f32_16x16x32_bf16 v[86:89], v[162:165], v[208:211], v[86:89]
	v_mfma_f32_16x16x32_bf16 v[82:85], v[170:173], v[208:211], v[82:85]
	v_mfma_f32_16x16x32_bf16 v[70:73], v[162:165], v[216:219], v[70:73]
	v_mfma_f32_16x16x32_bf16 v[66:69], v[170:173], v[216:219], v[66:69]
	v_mfma_f32_16x16x32_bf16 v[118:121], v[166:169], v[182:185], v[118:121]
	v_mfma_f32_16x16x32_bf16 v[114:117], v[174:177], v[182:185], v[114:117]
	v_mfma_f32_16x16x32_bf16 v[102:105], v[166:169], v[204:207], v[102:105]
	v_mfma_f32_16x16x32_bf16 v[98:101], v[174:177], v[204:207], v[98:101]
	v_mfma_f32_16x16x32_bf16 v[86:89], v[166:169], v[212:215], v[86:89]
	v_mfma_f32_16x16x32_bf16 v[82:85], v[174:177], v[212:215], v[82:85]
	v_mfma_f32_16x16x32_bf16 v[70:73], v[166:169], v[220:223], v[70:73]
	v_mfma_f32_16x16x32_bf16 v[66:69], v[174:177], v[220:223], v[66:69]
	s_setprio 0
	s_barrier
; #define PG8_STAGE(bufoff, gbase, voff) do { _Pragma("unroll") for (int _i = 0; _i < 2; ++_i) \
;         __builtin_amdgcn_global_load_lds((const unsigned*)((const char*)(gbase) + (voff)[_i]), (LAS unsigned*)(lds + (bufoff) + ldsw + _i * 8192), 16, 0, 0); } while (0)
; #define PG8_LDA(dst, b, h) do { _Pragma("unroll") for (int m = 0; m < 4; ++m) _Pragma("unroll") for (int k = 0; k < 2; ++k) dst[m][k] = *(const LAS bf16x8*)(lds + PG8_SA(b, h) + aoff + m * 2048 + k * 1024); } while (0)
; #define PG8_MMA(ai, bj, At, Bt) do { __builtin_amdgcn_s_setprio(1); _Pragma("unroll") for (int m = 0; m < 4; ++m) _Pragma("unroll") for (int n = 0; n < 2; ++n) _Pragma("unroll") for (int k = 0; k < 2; ++k) \
;         acc[ai][bj][m][n] = __builtin_amdgcn_mfma_f32_16x16x32_bf16(Bt[n][k], At[m][k], acc[ai][bj][m][n], 0, 0, 0); __builtin_amdgcn_s_setprio(0); } while (0)
; #define PG8_WAIT_V(n) asm volatile("s_waitcnt vmcnt(" #n ")" ::: "memory")
; #define PG8_WAIT_L(n) asm volatile("s_waitcnt lgkmcnt(" #n ")" ::: "memory")
; #define PG8_BAR __builtin_amdgcn_s_barrier()
; #define PG8_SCHED __builtin_amdgcn_sched_barrier(0)
; template <class Epi, class Sched, bool ALIGN_EPI = false, bool SP2 = false>
; __device__ __forceinline__ void gemm_phase(LAS unsigned char* lds, const Gemm g, const Sched& S, const Epi& E, const int tid_) {
;     ...
;             PG8_LDA(At, 1, 1); PG8_STAGE(PG8_SB(1, 0), b3, voffB); PG8_STAGE(PG8_SB(1, 1), b3 + hstep, voffB); PG8_STAGE(PG8_SA(1, 0), a3, voffA);
;             PG8_WAIT_V(8); PG8_WAIT_L(0); PG8_BAR; PG8_MMA(1, 0, At, B0); PG8_MMA(1, 1, At, B1); PG8_BAR; PG8_SCHED;
	s_add_i32 s50, s68, s55
	s_add_i32 m0, s50, 0xffffff80
	ds_read_b128 v[178:181], v145 offset:49152
	ds_read_b128 v[182:185], v145 offset:50176
	ds_read_b128 v[200:203], v145 offset:51200
	ds_read_b128 v[204:207], v145 offset:52224
	ds_read_b128 v[208:211], v145 offset:53248
	ds_read_b128 v[212:215], v145 offset:54272
	ds_read_b128 v[216:219], v145 offset:55296
	ds_read_b128 v[220:223], v145 offset:56320
	global_load_lds_dwordx4 v0, s[48:49] offset:128
	s_add_i32 m0, s50, 0x2000
	s_add_u32 s48, s48, 0x80080
	v_lshl_add_u64 v[140:141], v[192:193], 0, s[96:97]
	s_addc_u32 s49, s49, 0
	s_add_i32 s50, s69, s55
	global_load_lds_dwordx4 v[140:141], off
	s_mov_b32 m0, s50
	s_nop 0
	global_load_lds_dwordx4 v0, s[48:49]
	s_add_i32 m0, s50, 0x2000
	s_nop 0
	global_load_lds_dwordx4 v134, s[48:49]
	v_lshl_add_u64 v[140:141], v[224:225], 0, s[96:97]
	s_mov_b32 m0, s60
	s_nop 0
	global_load_lds_dwordx4 v[140:141], off
	v_lshl_add_u64 v[140:141], v[236:237], 0, s[96:97]
	s_mov_b32 m0, s61
	s_nop 0
	global_load_lds_dwordx4 v[140:141], off
	s_waitcnt vmcnt(8)
	s_waitcnt lgkmcnt(0)
	s_barrier
	s_setprio 1
	s_waitcnt lgkmcnt(0)
	v_mfma_f32_16x16x32_bf16 v[62:65], v[146:149], v[178:181], v[62:65]
	v_mfma_f32_16x16x32_bf16 v[58:61], v[154:157], v[178:181], v[58:61]
	v_mfma_f32_16x16x32_bf16 v[46:49], v[146:149], v[200:203], v[46:49]
	v_mfma_f32_16x16x32_bf16 v[42:45], v[154:157], v[200:203], v[42:45]
	v_mfma_f32_16x16x32_bf16 v[30:33], v[146:149], v[208:211], v[30:33]
	v_mfma_f32_16x16x32_bf16 v[26:29], v[154:157], v[208:211], v[26:29]
	v_mfma_f32_16x16x32_bf16 v[14:17], v[146:149], v[216:219], v[14:17]
	v_mfma_f32_16x16x32_bf16 v[10:13], v[154:157], v[216:219], v[10:13]
	v_mfma_f32_16x16x32_bf16 v[62:65], v[150:153], v[182:185], v[62:65]
	v_mfma_f32_16x16x32_bf16 v[58:61], v[158:161], v[182:185], v[58:61]
	v_mfma_f32_16x16x32_bf16 v[46:49], v[150:153], v[204:207], v[46:49]
	v_mfma_f32_16x16x32_bf16 v[42:45], v[158:161], v[204:207], v[42:45]
	v_mfma_f32_16x16x32_bf16 v[30:33], v[150:153], v[212:215], v[30:33]
	v_mfma_f32_16x16x32_bf16 v[26:29], v[158:161], v[212:215], v[26:29]
	v_mfma_f32_16x16x32_bf16 v[14:17], v[150:153], v[220:223], v[14:17]
	v_mfma_f32_16x16x32_bf16 v[10:13], v[158:161], v[220:223], v[10:13]
	s_setprio 0
	s_setprio 1
	v_mfma_f32_16x16x32_bf16 v[54:57], v[162:165], v[178:181], v[54:57]
	v_mfma_f32_16x16x32_bf16 v[50:53], v[170:173], v[178:181], v[50:53]
	v_mfma_f32_16x16x32_bf16 v[38:41], v[162:165], v[200:203], v[38:41]
	v_mfma_f32_16x16x32_bf16 v[34:37], v[170:173], v[200:203], v[34:37]
	v_mfma_f32_16x16x32_bf16 v[22:25], v[162:165], v[208:211], v[22:25]
	v_mfma_f32_16x16x32_bf16 v[18:21], v[170:173], v[208:211], v[18:21]
	v_mfma_f32_16x16x32_bf16 v[6:9], v[162:165], v[216:219], v[6:9]
	v_mfma_f32_16x16x32_bf16 v[2:5], v[170:173], v[216:219], v[2:5]
	v_mfma_f32_16x16x32_bf16 v[54:57], v[166:169], v[182:185], v[54:57]
	v_mfma_f32_16x16x32_bf16 v[50:53], v[174:177], v[182:185], v[50:53]
	v_mfma_f32_16x16x32_bf16 v[38:41], v[166:169], v[204:207], v[38:41]
	v_mfma_f32_16x16x32_bf16 v[34:37], v[174:177], v[204:207], v[34:37]
	v_mfma_f32_16x16x32_bf16 v[22:25], v[166:169], v[212:215], v[22:25]
	v_mfma_f32_16x16x32_bf16 v[18:21], v[174:177], v[212:215], v[18:21]
	v_mfma_f32_16x16x32_bf16 v[6:9], v[166:169], v[220:223], v[6:9]
	v_mfma_f32_16x16x32_bf16 v[2:5], v[174:177], v[220:223], v[2:5]
	s_setprio 0
	s_barrier
	s_add_i32 s67, s67, 2
	s_add_u32 s46, s46, 0x100
	s_addc_u32 s47, s47, 0
	s_add_u32 s65, s65, 0x100
	s_addc_u32 s66, s66, 0
	s_cmp_gt_u32 s67, 29
	s_cbranch_scc0 .LBB0_34
	s_and_b64 vcc, exec, s[12:13]
	s_cbranch_vccz .LBB0_37
	s_barrier

; #define PG8_STAGE(bufoff, gbase, voff) do { _Pragma("unroll") for (int _i = 0; _i < 2; ++_i) \
;         __builtin_amdgcn_global_load_lds((const unsigned*)((const char*)(gbase) + (voff)[_i]), (LAS unsigned*)(lds + (bufoff) + ldsw + _i * 8192), 16, 0, 0); } while (0)
; #define PG8_LDA(dst, b, h) do { _Pragma("unroll") for (int m = 0; m < 4; ++m) _Pragma("unroll") for (int k = 0; k < 2; ++k) dst[m][k] = *(const LAS bf16x8*)(lds + PG8_SA(b, h) + aoff + m * 2048 + k * 1024); } while (0)
; #define PG8_LDB(dst, b, h) do { _Pragma("unroll") for (int n = 0; n < 2; ++n) _Pragma("unroll") for (int k = 0; k < 2; ++k) dst[n][k] = *(const LAS bf16x8*)(lds + PG8_SB(b, h) + boff + n * 2048 + k * 1024); } while (0)
; #define PG8_MMA(ai, bj, At, Bt) do { __builtin_amdgcn_s_setprio(1); _Pragma("unroll") for (int m = 0; m < 4; ++m) _Pragma("unroll") for (int n = 0; n < 2; ++n) _Pragma("unroll") for (int k = 0; k < 2; ++k) \
;         acc[ai][bj][m][n] = __builtin_amdgcn_mfma_f32_16x16x32_bf16(Bt[n][k], At[m][k], acc[ai][bj][m][n], 0, 0, 0); __builtin_amdgcn_s_setprio(0); } while (0)
; #define PG8_WAIT_V(n) asm volatile("s_waitcnt vmcnt(" #n ")" ::: "memory")
; #define PG8_WAIT_L(n) asm volatile("s_waitcnt lgkmcnt(" #n ")" ::: "memory")
; #define PG8_BAR __builtin_amdgcn_s_barrier()
; #define PG8_SCHED __builtin_amdgcn_sched_barrier(0)
; template <class Epi, class Sched, bool ALIGN_EPI = false, bool SP2 = false>
; __device__ __forceinline__ void gemm_phase(LAS unsigned char* lds, const Gemm g, const Sched& S, const Epi& E, const int tid_) {
;     ...
;             if constexpr (SP2) {
;             PG8_LDB(B0, 0, 0); PG8_LDB(B1, 0, 1); PG8_SCHED; PG8_LDA(At, 0, 0); PG8_STAGE(PG8_SA(1, 1), a1 + hstep, voffA);
;             PG8_WAIT_V(8); PG8_WAIT_L(0); PG8_BAR; PG8_MMA(0, 0, At, B0); PG8_MMA(0, 1, At, B1); PG8_BAR; PG8_SCHED;
;             PG8_LDA(At, 0, 1); PG8_STAGE(PG8_SB(0, 0), b2, voffB); PG8_STAGE(PG8_SB(0, 1), b2 + hstep, voffB); PG8_STAGE(PG8_SA(0, 0), a2, voffA);
;             PG8_WAIT_V(8); PG8_WAIT_L(0); PG8_BAR; PG8_MMA(1, 0, At, B0); PG8_MMA(1, 1, At, B1); PG8_BAR; PG8_SCHED;
.LBB0_70:
	s_add_u32 s48, s46, 0x100
	s_addc_u32 s49, s47, 0
	s_add_i32 s70, 0, 0x10000
	s_cmp_eq_u32 s69, 28
	s_cselect_b32 s55, s17, s49
	s_cselect_b32 s54, s21, s48
	s_cselect_b32 s51, s15, s68
	s_cselect_b32 s50, s66, s67
	s_add_i32 s71, 0, 0x14000
	v_add_u32_e32 v148, s70, v157
	v_add_u32_e32 v168, s71, v157
	ds_read_b128 v[130:133], v148
	ds_read_b128 v[134:137], v148 offset:1024
	ds_read_b128 v[138:141], v148 offset:2048
	ds_read_b128 v[148:151], v148 offset:3072
	ds_read_b128 v[152:155], v168
	ds_read_b128 v[160:163], v168 offset:1024
	ds_read_b128 v[164:167], v168 offset:2048
	ds_read_b128 v[168:171], v168 offset:3072
	s_add_i32 m0, s45, 0xc000
	ds_read_b128 v[172:175], v159
	ds_read_b128 v[176:179], v159 offset:1024
	ds_read_b128 v[180:183], v159 offset:2048
	ds_read_b128 v[200:203], v159 offset:3072
	ds_read_b128 v[204:207], v159 offset:4096
	ds_read_b128 v[208:211], v159 offset:5120
	ds_read_b128 v[212:215], v159 offset:6144
	ds_read_b128 v[216:219], v159 offset:7168
	global_load_lds_dwordx4 v144, s[46:47]
	s_add_i32 m0, s45, 0xe000
	s_nop 0
	global_load_lds_dwordx4 v146, s[46:47]
	s_waitcnt vmcnt(8)
	s_waitcnt lgkmcnt(0)
	s_barrier
	s_setprio 1
	s_waitcnt lgkmcnt(0)
	v_mfma_f32_16x16x32_bf16 v[126:129], v[130:133], v[172:175], v[126:129]
	v_mfma_f32_16x16x32_bf16 v[122:125], v[138:141], v[172:175], v[122:125]
	v_mfma_f32_16x16x32_bf16 v[118:121], v[130:133], v[180:183], v[118:121]
	v_mfma_f32_16x16x32_bf16 v[106:109], v[138:141], v[180:183], v[106:109]
	v_mfma_f32_16x16x32_bf16 v[102:105], v[130:133], v[204:207], v[102:105]
	v_mfma_f32_16x16x32_bf16 v[90:93], v[138:141], v[204:207], v[90:93]
	v_mfma_f32_16x16x32_bf16 v[86:89], v[130:133], v[212:215], v[86:89]
	v_mfma_f32_16x16x32_bf16 v[74:77], v[138:141], v[212:215], v[74:77]
	v_mfma_f32_16x16x32_bf16 v[126:129], v[134:137], v[176:179], v[126:129]
	v_mfma_f32_16x16x32_bf16 v[122:125], v[148:151], v[176:179], v[122:125]
	v_mfma_f32_16x16x32_bf16 v[118:121], v[134:137], v[200:203], v[118:121]
	v_mfma_f32_16x16x32_bf16 v[106:109], v[148:151], v[200:203], v[106:109]
	v_mfma_f32_16x16x32_bf16 v[102:105], v[134:137], v[208:211], v[102:105]
	v_mfma_f32_16x16x32_bf16 v[90:93], v[148:151], v[208:211], v[90:93]
	v_mfma_f32_16x16x32_bf16 v[86:89], v[134:137], v[216:219], v[86:89]
	v_mfma_f32_16x16x32_bf16 v[74:77], v[148:151], v[216:219], v[74:77]
	s_setprio 0
	s_setprio 1
	v_mfma_f32_16x16x32_bf16 v[114:117], v[152:155], v[172:175], v[114:117]
	v_mfma_f32_16x16x32_bf16 v[110:113], v[164:167], v[172:175], v[110:113]
	v_mfma_f32_16x16x32_bf16 v[98:101], v[152:155], v[180:183], v[98:101]
	v_mfma_f32_16x16x32_bf16 v[94:97], v[164:167], v[180:183], v[94:97]
	v_mfma_f32_16x16x32_bf16 v[82:85], v[152:155], v[204:207], v[82:85]
	v_mfma_f32_16x16x32_bf16 v[78:81], v[164:167], v[204:207], v[78:81]
	v_mfma_f32_16x16x32_bf16 v[70:73], v[152:155], v[212:215], v[70:73]
	v_mfma_f32_16x16x32_bf16 v[66:69], v[164:167], v[212:215], v[66:69]
	v_mfma_f32_16x16x32_bf16 v[114:117], v[160:163], v[176:179], v[114:117]
	v_mfma_f32_16x16x32_bf16 v[110:113], v[168:171], v[176:179], v[110:113]
	v_mfma_f32_16x16x32_bf16 v[98:101], v[160:163], v[200:203], v[98:101]
	v_mfma_f32_16x16x32_bf16 v[94:97], v[168:171], v[200:203], v[94:97]
	v_mfma_f32_16x16x32_bf16 v[82:85], v[160:163], v[208:211], v[82:85]
	v_mfma_f32_16x16x32_bf16 v[78:81], v[168:171], v[208:211], v[78:81]
	v_mfma_f32_16x16x32_bf16 v[70:73], v[160:163], v[216:219], v[70:73]
	v_mfma_f32_16x16x32_bf16 v[66:69], v[168:171], v[216:219], v[66:69]
	s_setprio 0
	s_barrier
	s_add_i32 s46, s70, s57
	s_mov_b32 m0, s46
	ds_read_b128 v[172:175], v159 offset:16384
	ds_read_b128 v[176:179], v159 offset:17408
	ds_read_b128 v[180:183], v159 offset:18432
	ds_read_b128 v[200:203], v159 offset:19456
	ds_read_b128 v[204:207], v159 offset:20480
	ds_read_b128 v[208:211], v159 offset:21504
	ds_read_b128 v[212:215], v159 offset:22528
	ds_read_b128 v[216:219], v159 offset:23552
	global_load_lds_dwordx4 v0, s[50:51]
	s_add_i32 m0, s46, 0x2000
	s_add_u32 s46, s50, 0x80000
	v_lshl_add_u64 v[192:193], s[50:51], 0, v[142:143]
	s_addc_u32 s47, s51, 0
	s_add_i32 s70, s71, s57
	global_load_lds_dwordx4 v142, s[50:51]
	s_mov_b32 m0, s70
	s_nop 0
	global_load_lds_dwordx4 v0, s[46:47]
	s_add_i32 m0, s70, 0x2000
	s_nop 0
	global_load_lds_dwordx4 v142, s[46:47]
	s_mov_b32 m0, s45
	s_nop 0
	global_load_lds_dwordx4 v0, s[54:55]
	s_mov_b32 m0, s58
	s_nop 0
	global_load_lds_dwordx4 v142, s[54:55]
	s_waitcnt vmcnt(8)
	s_waitcnt lgkmcnt(0)
	s_barrier
	s_setprio 1
	s_waitcnt lgkmcnt(0)
	v_mfma_f32_16x16x32_bf16 v[62:65], v[130:133], v[172:175], v[62:65]
	v_mfma_f32_16x16x32_bf16 v[58:61], v[138:141], v[172:175], v[58:61]
	v_mfma_f32_16x16x32_bf16 v[54:57], v[130:133], v[180:183], v[54:57]
	v_mfma_f32_16x16x32_bf16 v[42:45], v[138:141], v[180:183], v[42:45]
	v_mfma_f32_16x16x32_bf16 v[38:41], v[130:133], v[204:207], v[38:41]
	v_mfma_f32_16x16x32_bf16 v[26:29], v[138:141], v[204:207], v[26:29]
	v_mfma_f32_16x16x32_bf16 v[22:25], v[130:133], v[212:215], v[22:25]
	v_mfma_f32_16x16x32_bf16 v[10:13], v[138:141], v[212:215], v[10:13]
	v_mfma_f32_16x16x32_bf16 v[62:65], v[134:137], v[176:179], v[62:65]
	v_mfma_f32_16x16x32_bf16 v[58:61], v[148:151], v[176:179], v[58:61]
	v_mfma_f32_16x16x32_bf16 v[54:57], v[134:137], v[200:203], v[54:57]
	v_mfma_f32_16x16x32_bf16 v[42:45], v[148:151], v[200:203], v[42:45]
	v_mfma_f32_16x16x32_bf16 v[38:41], v[134:137], v[208:211], v[38:41]
	v_mfma_f32_16x16x32_bf16 v[26:29], v[148:151], v[208:211], v[26:29]
	v_mfma_f32_16x16x32_bf16 v[22:25], v[134:137], v[216:219], v[22:25]
	v_mfma_f32_16x16x32_bf16 v[10:13], v[148:151], v[216:219], v[10:13]
	s_setprio 0
	s_setprio 1
	v_mfma_f32_16x16x32_bf16 v[50:53], v[152:155], v[172:175], v[50:53]
	v_mfma_f32_16x16x32_bf16 v[46:49], v[164:167], v[172:175], v[46:49]
	v_mfma_f32_16x16x32_bf16 v[34:37], v[152:155], v[180:183], v[34:37]
	v_mfma_f32_16x16x32_bf16 v[30:33], v[164:167], v[180:183], v[30:33]
	v_mfma_f32_16x16x32_bf16 v[18:21], v[152:155], v[204:207], v[18:21]
	v_mfma_f32_16x16x32_bf16 v[14:17], v[164:167], v[204:207], v[14:17]
	v_mfma_f32_16x16x32_bf16 v[6:9], v[152:155], v[212:215], v[6:9]
	v_mfma_f32_16x16x32_bf16 v[2:5], v[164:167], v[212:215], v[2:5]
	v_mfma_f32_16x16x32_bf16 v[50:53], v[160:163], v[176:179], v[50:53]
	v_mfma_f32_16x16x32_bf16 v[46:49], v[168:171], v[176:179], v[46:49]
	v_mfma_f32_16x16x32_bf16 v[34:37], v[160:163], v[200:203], v[34:37]
	v_mfma_f32_16x16x32_bf16 v[30:33], v[168:171], v[200:203], v[30:33]
	v_mfma_f32_16x16x32_bf16 v[18:21], v[160:163], v[208:211], v[18:21]
	v_mfma_f32_16x16x32_bf16 v[14:17], v[168:171], v[208:211], v[14:17]
	v_mfma_f32_16x16x32_bf16 v[6:9], v[160:163], v[216:219], v[6:9]
	v_mfma_f32_16x16x32_bf16 v[2:5], v[168:171], v[216:219], v[2:5]
	s_setprio 0
	s_barrier
; #define PG8_STAGE(bufoff, gbase, voff) do { _Pragma("unroll") for (int _i = 0; _i < 2; ++_i) \
;         __builtin_amdgcn_global_load_lds((const unsigned*)((const char*)(gbase) + (voff)[_i]), (LAS unsigned*)(lds + (bufoff) + ldsw + _i * 8192), 16, 0, 0); } while (0)
; #define PG8_LDA(dst, b, h) do { _Pragma("unroll") for (int m = 0; m < 4; ++m) _Pragma("unroll") for (int k = 0; k < 2; ++k) dst[m][k] = *(const LAS bf16x8*)(lds + PG8_SA(b, h) + aoff + m * 2048 + k * 1024); } while (0)
; #define PG8_LDB(dst, b, h) do { _Pragma("unroll") for (int n = 0; n < 2; ++n) _Pragma("unroll") for (int k = 0; k < 2; ++k) dst[n][k] = *(const LAS bf16x8*)(lds + PG8_SB(b, h) + boff + n * 2048 + k * 1024); } while (0)
; #define PG8_MMA(ai, bj, At, Bt) do { __builtin_amdgcn_s_setprio(1); _Pragma("unroll") for (int m = 0; m < 4; ++m) _Pragma("unroll") for (int n = 0; n < 2; ++n) _Pragma("unroll") for (int k = 0; k < 2; ++k) \
;         acc[ai][bj][m][n] = __builtin_amdgcn_mfma_f32_16x16x32_bf16(Bt[n][k], At[m][k], acc[ai][bj][m][n], 0, 0, 0); __builtin_amdgcn_s_setprio(0); } while (0)
; #define PG8_WAIT_V(n) asm volatile("s_waitcnt vmcnt(" #n ")" ::: "memory")
; #define PG8_WAIT_L(n) asm volatile("s_waitcnt lgkmcnt(" #n ")" ::: "memory")
; #define PG8_BAR __builtin_amdgcn_s_barrier()
; #define PG8_SCHED __builtin_amdgcn_sched_barrier(0)
; template <class Epi, class Sched, bool ALIGN_EPI = false, bool SP2 = false>
; __device__ __forceinline__ void gemm_phase(LAS unsigned char* lds, const Gemm g, const Sched& S, const Epi& E, const int tid_) {
;     ...
;             PG8_LDB(B0, 1, 0); PG8_LDB(B1, 1, 1); PG8_SCHED; PG8_LDA(At, 1, 0); PG8_STAGE(PG8_SA(0, 1), a2 + hstep, voffA);
;             PG8_WAIT_V(8); PG8_WAIT_L(0); PG8_BAR; PG8_MMA(0, 0, At, B0); PG8_MMA(0, 1, At, B1); PG8_BAR; PG8_SCHED;
;             PG8_LDA(At, 1, 1); PG8_STAGE(PG8_SB(1, 0), b3, voffB); PG8_STAGE(PG8_SB(1, 1), b3 + hstep, voffB); PG8_STAGE(PG8_SA(1, 0), a3, voffA);
;             PG8_WAIT_V(8); PG8_WAIT_L(0); PG8_BAR; PG8_MMA(1, 0, At, B0); PG8_MMA(1, 1, At, B1); PG8_BAR; PG8_SCHED;
	s_add_i32 s70, 0, 0x18000
	s_add_i32 s71, 0, 0x1c000
	v_add_u32_e32 v148, s70, v157
	v_add_u32_e32 v168, s71, v157
	ds_read_b128 v[130:133], v148
	ds_read_b128 v[134:137], v148 offset:1024
	ds_read_b128 v[138:141], v148 offset:2048
	ds_read_b128 v[148:151], v148 offset:3072
	ds_read_b128 v[152:155], v168
	ds_read_b128 v[160:163], v168 offset:1024
	ds_read_b128 v[164:167], v168 offset:2048
	ds_read_b128 v[168:171], v168 offset:3072
	s_add_u32 s46, s54, 0x80000
	s_addc_u32 s47, s55, 0
	s_mov_b32 m0, s59
	ds_read_b128 v[172:175], v159 offset:32768
	ds_read_b128 v[176:179], v159 offset:33792
	ds_read_b128 v[180:183], v159 offset:34816
	ds_read_b128 v[200:203], v159 offset:35840
	ds_read_b128 v[204:207], v159 offset:36864
	ds_read_b128 v[208:211], v159 offset:37888
	ds_read_b128 v[212:215], v159 offset:38912
	ds_read_b128 v[216:219], v159 offset:39936
	global_load_lds_dwordx4 v0, s[46:47]
	s_mov_b32 m0, s60
	s_nop 0
	global_load_lds_dwordx4 v142, s[46:47]
	s_waitcnt vmcnt(8)
	s_waitcnt lgkmcnt(0)
	s_barrier
	s_setprio 1
	s_waitcnt lgkmcnt(0)
	v_mfma_f32_16x16x32_bf16 v[126:129], v[130:133], v[172:175], v[126:129]
	v_mfma_f32_16x16x32_bf16 v[122:125], v[138:141], v[172:175], v[122:125]
	v_mfma_f32_16x16x32_bf16 v[118:121], v[130:133], v[180:183], v[118:121]
	v_mfma_f32_16x16x32_bf16 v[106:109], v[138:141], v[180:183], v[106:109]
	v_mfma_f32_16x16x32_bf16 v[102:105], v[130:133], v[204:207], v[102:105]
	v_mfma_f32_16x16x32_bf16 v[90:93], v[138:141], v[204:207], v[90:93]
	v_mfma_f32_16x16x32_bf16 v[86:89], v[130:133], v[212:215], v[86:89]
	v_mfma_f32_16x16x32_bf16 v[74:77], v[138:141], v[212:215], v[74:77]
	v_mfma_f32_16x16x32_bf16 v[126:129], v[134:137], v[176:179], v[126:129]
	v_mfma_f32_16x16x32_bf16 v[122:125], v[148:151], v[176:179], v[122:125]
	v_mfma_f32_16x16x32_bf16 v[118:121], v[134:137], v[200:203], v[118:121]
	v_mfma_f32_16x16x32_bf16 v[106:109], v[148:151], v[200:203], v[106:109]
	v_mfma_f32_16x16x32_bf16 v[102:105], v[134:137], v[208:211], v[102:105]
	v_mfma_f32_16x16x32_bf16 v[90:93], v[148:151], v[208:211], v[90:93]
	v_mfma_f32_16x16x32_bf16 v[86:89], v[134:137], v[216:219], v[86:89]
	v_mfma_f32_16x16x32_bf16 v[74:77], v[148:151], v[216:219], v[74:77]
	s_setprio 0
	s_setprio 1
	v_mfma_f32_16x16x32_bf16 v[114:117], v[152:155], v[172:175], v[114:117]
	v_mfma_f32_16x16x32_bf16 v[110:113], v[164:167], v[172:175], v[110:113]
	v_mfma_f32_16x16x32_bf16 v[98:101], v[152:155], v[180:183], v[98:101]
	v_mfma_f32_16x16x32_bf16 v[94:97], v[164:167], v[180:183], v[94:97]
	v_mfma_f32_16x16x32_bf16 v[82:85], v[152:155], v[204:207], v[82:85]
	v_mfma_f32_16x16x32_bf16 v[78:81], v[164:167], v[204:207], v[78:81]
	v_mfma_f32_16x16x32_bf16 v[70:73], v[152:155], v[212:215], v[70:73]
	v_mfma_f32_16x16x32_bf16 v[66:69], v[164:167], v[212:215], v[66:69]
	v_mfma_f32_16x16x32_bf16 v[114:117], v[160:163], v[176:179], v[114:117]
	v_mfma_f32_16x16x32_bf16 v[110:113], v[168:171], v[176:179], v[110:113]
	v_mfma_f32_16x16x32_bf16 v[98:101], v[160:163], v[200:203], v[98:101]
	v_mfma_f32_16x16x32_bf16 v[94:97], v[168:171], v[200:203], v[94:97]
	v_mfma_f32_16x16x32_bf16 v[82:85], v[160:163], v[208:211], v[82:85]
	v_mfma_f32_16x16x32_bf16 v[78:81], v[168:171], v[208:211], v[78:81]
	v_mfma_f32_16x16x32_bf16 v[70:73], v[160:163], v[216:219], v[70:73]
	v_mfma_f32_16x16x32_bf16 v[66:69], v[168:171], v[216:219], v[66:69]
	s_setprio 0
	s_barrier
	s_add_i32 s46, s70, s57
	s_add_i32 m0, s46, 0xffffff80
	ds_read_b128 v[172:175], v159 offset:49152
	ds_read_b128 v[176:179], v159 offset:50176
	ds_read_b128 v[180:183], v159 offset:51200
	ds_read_b128 v[200:203], v159 offset:52224
	ds_read_b128 v[204:207], v159 offset:53248
	ds_read_b128 v[208:211], v159 offset:54272
	ds_read_b128 v[212:215], v159 offset:55296
	ds_read_b128 v[216:219], v159 offset:56320
	global_load_lds_dwordx4 v0, s[50:51] offset:128
	s_add_i32 m0, s46, 0x2000
	s_add_u32 s46, s50, 0x80080
	v_lshl_add_u64 v[184:185], v[192:193], 0, s[96:97]
	s_addc_u32 s47, s51, 0
	s_add_i32 s50, s71, s57
	global_load_lds_dwordx4 v[184:185], off
	s_mov_b32 m0, s50
	s_nop 0
	global_load_lds_dwordx4 v0, s[46:47]
	s_add_i32 m0, s50, 0x2000
	s_nop 0
	global_load_lds_dwordx4 v142, s[46:47]
	s_add_i32 m0, s62, 0xffffff80
	s_nop 0
	global_load_lds_dwordx4 v0, s[54:55] offset:128
	s_add_i32 m0, s63, 0xffffff80
	s_nop 0
	global_load_lds_dwordx4 v142, s[54:55] offset:128
	s_waitcnt vmcnt(8)
	s_waitcnt lgkmcnt(0)
	s_barrier
	s_setprio 1
	s_waitcnt lgkmcnt(0)
	v_mfma_f32_16x16x32_bf16 v[62:65], v[130:133], v[172:175], v[62:65]
	v_mfma_f32_16x16x32_bf16 v[58:61], v[138:141], v[172:175], v[58:61]
	v_mfma_f32_16x16x32_bf16 v[54:57], v[130:133], v[180:183], v[54:57]
	v_mfma_f32_16x16x32_bf16 v[42:45], v[138:141], v[180:183], v[42:45]
	v_mfma_f32_16x16x32_bf16 v[38:41], v[130:133], v[204:207], v[38:41]
	v_mfma_f32_16x16x32_bf16 v[26:29], v[138:141], v[204:207], v[26:29]
	v_mfma_f32_16x16x32_bf16 v[22:25], v[130:133], v[212:215], v[22:25]
	v_mfma_f32_16x16x32_bf16 v[10:13], v[138:141], v[212:215], v[10:13]
	v_mfma_f32_16x16x32_bf16 v[62:65], v[134:137], v[176:179], v[62:65]
	v_mfma_f32_16x16x32_bf16 v[58:61], v[148:151], v[176:179], v[58:61]
	v_mfma_f32_16x16x32_bf16 v[54:57], v[134:137], v[200:203], v[54:57]
	v_mfma_f32_16x16x32_bf16 v[42:45], v[148:151], v[200:203], v[42:45]
	v_mfma_f32_16x16x32_bf16 v[38:41], v[134:137], v[208:211], v[38:41]
	v_mfma_f32_16x16x32_bf16 v[26:29], v[148:151], v[208:211], v[26:29]
	v_mfma_f32_16x16x32_bf16 v[22:25], v[134:137], v[216:219], v[22:25]
	v_mfma_f32_16x16x32_bf16 v[10:13], v[148:151], v[216:219], v[10:13]
	s_setprio 0
	s_setprio 1
	v_mfma_f32_16x16x32_bf16 v[50:53], v[152:155], v[172:175], v[50:53]
	v_mfma_f32_16x16x32_bf16 v[46:49], v[164:167], v[172:175], v[46:49]
	v_mfma_f32_16x16x32_bf16 v[34:37], v[152:155], v[180:183], v[34:37]
	v_mfma_f32_16x16x32_bf16 v[30:33], v[164:167], v[180:183], v[30:33]
	v_mfma_f32_16x16x32_bf16 v[18:21], v[152:155], v[204:207], v[18:21]
	v_mfma_f32_16x16x32_bf16 v[14:17], v[164:167], v[204:207], v[14:17]
	v_mfma_f32_16x16x32_bf16 v[6:9], v[152:155], v[212:215], v[6:9]
	v_mfma_f32_16x16x32_bf16 v[2:5], v[164:167], v[212:215], v[2:5]
	v_mfma_f32_16x16x32_bf16 v[50:53], v[160:163], v[176:179], v[50:53]
	v_mfma_f32_16x16x32_bf16 v[46:49], v[168:171], v[176:179], v[46:49]
	v_mfma_f32_16x16x32_bf16 v[34:37], v[160:163], v[200:203], v[34:37]
	v_mfma_f32_16x16x32_bf16 v[30:33], v[168:171], v[200:203], v[30:33]
	v_mfma_f32_16x16x32_bf16 v[18:21], v[160:163], v[208:211], v[18:21]
	v_mfma_f32_16x16x32_bf16 v[14:17], v[168:171], v[208:211], v[14:17]
	v_mfma_f32_16x16x32_bf16 v[6:9], v[160:163], v[216:219], v[6:9]
	v_mfma_f32_16x16x32_bf16 v[2:5], v[168:171], v[216:219], v[2:5]
	s_setprio 0
	s_barrier
	s_add_i32 s69, s69, 2
	s_add_u32 s67, s67, 0x100
	s_addc_u32 s68, s68, 0
	s_cmp_gt_u32 s69, 29
	s_mov_b64 s[46:47], s[48:49]
	s_cbranch_scc0 .LBB0_70
	s_and_b64 vcc, exec, s[12:13]
	s_cbranch_vccz .LBB0_73
	s_barrier

; #define PG8_STAGE(bufoff, gbase, voff) do { _Pragma("unroll") for (int _i = 0; _i < 2; ++_i) \
;         __builtin_amdgcn_global_load_lds((const unsigned*)((const char*)(gbase) + (voff)[_i]), (LAS unsigned*)(lds + (bufoff) + ldsw + _i * 8192), 16, 0, 0); } while (0)
; #define PG8_LDA(dst, b, h) do { _Pragma("unroll") for (int m = 0; m < 4; ++m) _Pragma("unroll") for (int k = 0; k < 2; ++k) dst[m][k] = *(const LAS bf16x8*)(lds + PG8_SA(b, h) + aoff + m * 2048 + k * 1024); } while (0)
; #define PG8_LDB(dst, b, h) do { _Pragma("unroll") for (int n = 0; n < 2; ++n) _Pragma("unroll") for (int k = 0; k < 2; ++k) dst[n][k] = *(const LAS bf16x8*)(lds + PG8_SB(b, h) + boff + n * 2048 + k * 1024); } while (0)
; #define PG8_MMA(ai, bj, At, Bt) do { __builtin_amdgcn_s_setprio(1); _Pragma("unroll") for (int m = 0; m < 4; ++m) _Pragma("unroll") for (int n = 0; n < 2; ++n) _Pragma("unroll") for (int k = 0; k < 2; ++k) \
;         acc[ai][bj][m][n] = __builtin_amdgcn_mfma_f32_16x16x32_bf16(Bt[n][k], At[m][k], acc[ai][bj][m][n], 0, 0, 0); __builtin_amdgcn_s_setprio(0); } while (0)
; #define PG8_WAIT_V(n) asm volatile("s_waitcnt vmcnt(" #n ")" ::: "memory")
; #define PG8_WAIT_L(n) asm volatile("s_waitcnt lgkmcnt(" #n ")" ::: "memory")
; #define PG8_BAR __builtin_amdgcn_s_barrier()
; #define PG8_SCHED __builtin_amdgcn_sched_barrier(0)
; template <class Epi, class Sched, bool ALIGN_EPI = false, bool SP2 = false>
; __device__ __forceinline__ void gemm_phase(LAS unsigned char* lds, const Gemm g, const Sched& S, const Epi& E, const int tid_) {
;     ...
;             if constexpr (SP2) {
;             PG8_LDB(B0, 0, 0); PG8_LDB(B1, 0, 1); PG8_SCHED; PG8_LDA(At, 0, 0); PG8_STAGE(PG8_SA(1, 1), a1 + hstep, voffA);
;             PG8_WAIT_V(8); PG8_WAIT_L(0); PG8_BAR; PG8_MMA(0, 0, At, B0); PG8_MMA(0, 1, At, B1); PG8_BAR; PG8_SCHED;
;             PG8_LDA(At, 0, 1); PG8_STAGE(PG8_SB(0, 0), b2, voffB); PG8_STAGE(PG8_SB(0, 1), b2 + hstep, voffB); PG8_STAGE(PG8_SA(0, 0), a2, voffA);
;             PG8_WAIT_V(8); PG8_WAIT_L(0); PG8_BAR; PG8_MMA(1, 0, At, B0); PG8_MMA(1, 1, At, B1); PG8_BAR; PG8_SCHED;
.LBB0_96:
	s_add_u32 s54, s50, 0xfffc0080
	s_addc_u32 s55, s51, -1
	s_add_i32 s72, 0, 0x10000
	s_cmp_eq_u32 s71, 12
	s_cselect_b32 s57, s19, s55
	s_cselect_b32 s56, s20, s54
	s_cselect_b32 s55, s17, s70
	s_cselect_b32 s54, s21, s69
	s_add_i32 s74, 0, 0x14000
	v_add_u32_e32 v142, s72, v177
	v_add_u32_e32 v162, s74, v177
	ds_read_b128 v[130:133], v142
	ds_read_b128 v[134:137], v142 offset:1024
	ds_read_b128 v[138:141], v142 offset:2048
	ds_read_b128 v[142:145], v142 offset:3072
	s_nop 0
	ds_read_b128 v[146:149], v162
	ds_read_b128 v[154:157], v162 offset:1024
	ds_read_b128 v[158:161], v162 offset:2048
	ds_read_b128 v[162:165], v162 offset:3072
	s_add_i32 m0, s49, 0xc000
	ds_read_b128 v[180:183], v179
	ds_read_b128 v[206:209], v179 offset:1024
	ds_read_b128 v[210:213], v179 offset:2048
	ds_read_b128 v[214:217], v179 offset:3072
	ds_read_b128 v[218:221], v179 offset:4096
	ds_read_b128 v[222:225], v179 offset:5120
	ds_read_b128 v[242:245], v179 offset:6144
	ds_read_b128 v[246:249], v179 offset:7168
	global_load_lds_dwordx4 v150, s[50:51]
	s_add_i32 m0, s49, 0xe000
	s_nop 0
	global_load_lds_dwordx4 v152, s[50:51]
	s_waitcnt vmcnt(8)
	s_waitcnt lgkmcnt(0)
	s_barrier
	s_setprio 1
	s_waitcnt lgkmcnt(0)
	v_mfma_f32_16x16x32_bf16 v[126:129], v[130:133], v[180:183], v[126:129]
	v_mfma_f32_16x16x32_bf16 v[122:125], v[138:141], v[180:183], v[122:125]
	v_mfma_f32_16x16x32_bf16 v[118:121], v[130:133], v[210:213], v[118:121]
	v_mfma_f32_16x16x32_bf16 v[114:117], v[138:141], v[210:213], v[114:117]
	v_mfma_f32_16x16x32_bf16 v[98:101], v[130:133], v[218:221], v[98:101]
	v_mfma_f32_16x16x32_bf16 v[90:93], v[138:141], v[218:221], v[90:93]
	v_mfma_f32_16x16x32_bf16 v[82:85], v[130:133], v[242:245], v[82:85]
	v_mfma_f32_16x16x32_bf16 v[74:77], v[138:141], v[242:245], v[74:77]
	v_mfma_f32_16x16x32_bf16 v[126:129], v[134:137], v[206:209], v[126:129]
	v_mfma_f32_16x16x32_bf16 v[122:125], v[142:145], v[206:209], v[122:125]
	v_mfma_f32_16x16x32_bf16 v[118:121], v[134:137], v[214:217], v[118:121]
	v_mfma_f32_16x16x32_bf16 v[114:117], v[142:145], v[214:217], v[114:117]
	v_mfma_f32_16x16x32_bf16 v[98:101], v[134:137], v[222:225], v[98:101]
	v_mfma_f32_16x16x32_bf16 v[90:93], v[142:145], v[222:225], v[90:93]
	v_mfma_f32_16x16x32_bf16 v[82:85], v[134:137], v[246:249], v[82:85]
	v_mfma_f32_16x16x32_bf16 v[74:77], v[142:145], v[246:249], v[74:77]
	s_setprio 0
	s_setprio 1
	v_mfma_f32_16x16x32_bf16 v[110:113], v[146:149], v[180:183], v[110:113]
	v_mfma_f32_16x16x32_bf16 v[106:109], v[158:161], v[180:183], v[106:109]
	v_mfma_f32_16x16x32_bf16 v[102:105], v[146:149], v[210:213], v[102:105]
	v_mfma_f32_16x16x32_bf16 v[94:97], v[158:161], v[210:213], v[94:97]
	v_mfma_f32_16x16x32_bf16 v[86:89], v[146:149], v[218:221], v[86:89]
	v_mfma_f32_16x16x32_bf16 v[78:81], v[158:161], v[218:221], v[78:81]
	v_mfma_f32_16x16x32_bf16 v[70:73], v[146:149], v[242:245], v[70:73]
	v_mfma_f32_16x16x32_bf16 v[66:69], v[158:161], v[242:245], v[66:69]
	v_mfma_f32_16x16x32_bf16 v[110:113], v[154:157], v[206:209], v[110:113]
	v_mfma_f32_16x16x32_bf16 v[106:109], v[162:165], v[206:209], v[106:109]
	v_mfma_f32_16x16x32_bf16 v[102:105], v[154:157], v[214:217], v[102:105]
	v_mfma_f32_16x16x32_bf16 v[94:97], v[162:165], v[214:217], v[94:97]
	v_mfma_f32_16x16x32_bf16 v[86:89], v[154:157], v[222:225], v[86:89]
	v_mfma_f32_16x16x32_bf16 v[78:81], v[162:165], v[222:225], v[78:81]
	v_mfma_f32_16x16x32_bf16 v[70:73], v[154:157], v[246:249], v[70:73]
	v_mfma_f32_16x16x32_bf16 v[66:69], v[162:165], v[246:249], v[66:69]
	s_setprio 0
	s_barrier
	s_add_i32 s72, s72, s60
	s_mov_b32 m0, s72
	ds_read_b128 v[180:183], v179 offset:16384
	ds_read_b128 v[206:209], v179 offset:17408
	ds_read_b128 v[210:213], v179 offset:18432
	ds_read_b128 v[214:217], v179 offset:19456
	ds_read_b128 v[218:221], v179 offset:20480
	ds_read_b128 v[222:225], v179 offset:21504
	ds_read_b128 v[242:245], v179 offset:22528
	ds_read_b128 v[246:249], v179 offset:23552
	global_load_lds_dwordx4 v0, s[54:55]
	s_add_i32 m0, s72, 0x2000
	s_add_u32 s72, s54, 0x40000
	v_lshl_add_u64 v[236:237], s[54:55], 0, v[204:205]
	s_addc_u32 s73, s55, 0
	s_add_i32 s74, s74, s60
	global_load_lds_dwordx4 v204, s[54:55]
	s_mov_b32 m0, s74
	v_lshl_add_u64 v[252:253], s[56:57], 0, v[202:203]
	global_load_lds_dwordx4 v0, s[72:73]
	s_add_i32 m0, s74, 0x2000
	s_nop 0
	global_load_lds_dwordx4 v204, s[72:73]
	v_lshl_add_u64 v[250:251], s[56:57], 0, v[200:201]
	s_mov_b32 m0, s49
	s_nop 0
	global_load_lds_dwordx4 v200, s[56:57]
	s_mov_b32 m0, s61
	s_nop 0
	global_load_lds_dwordx4 v202, s[56:57]
	s_waitcnt vmcnt(8)
	s_waitcnt lgkmcnt(0)
	s_barrier
; #define PG8_STAGE(bufoff, gbase, voff) do { _Pragma("unroll") for (int _i = 0; _i < 2; ++_i) \
;         __builtin_amdgcn_global_load_lds((const unsigned*)((const char*)(gbase) + (voff)[_i]), (LAS unsigned*)(lds + (bufoff) + ldsw + _i * 8192), 16, 0, 0); } while (0)
; #define PG8_LDA(dst, b, h) do { _Pragma("unroll") for (int m = 0; m < 4; ++m) _Pragma("unroll") for (int k = 0; k < 2; ++k) dst[m][k] = *(const LAS bf16x8*)(lds + PG8_SA(b, h) + aoff + m * 2048 + k * 1024); } while (0)
; #define PG8_LDB(dst, b, h) do { _Pragma("unroll") for (int n = 0; n < 2; ++n) _Pragma("unroll") for (int k = 0; k < 2; ++k) dst[n][k] = *(const LAS bf16x8*)(lds + PG8_SB(b, h) + boff + n * 2048 + k * 1024); } while (0)
; #define PG8_MMA(ai, bj, At, Bt) do { __builtin_amdgcn_s_setprio(1); _Pragma("unroll") for (int m = 0; m < 4; ++m) _Pragma("unroll") for (int n = 0; n < 2; ++n) _Pragma("unroll") for (int k = 0; k < 2; ++k) \
;         acc[ai][bj][m][n] = __builtin_amdgcn_mfma_f32_16x16x32_bf16(Bt[n][k], At[m][k], acc[ai][bj][m][n], 0, 0, 0); __builtin_amdgcn_s_setprio(0); } while (0)
; #define PG8_WAIT_V(n) asm volatile("s_waitcnt vmcnt(" #n ")" ::: "memory")
; #define PG8_WAIT_L(n) asm volatile("s_waitcnt lgkmcnt(" #n ")" ::: "memory")
; #define PG8_BAR __builtin_amdgcn_s_barrier()
; #define PG8_SCHED __builtin_amdgcn_sched_barrier(0)
; template <class Epi, class Sched, bool ALIGN_EPI = false, bool SP2 = false>
; __device__ __forceinline__ void gemm_phase(LAS unsigned char* lds, const Gemm g, const Sched& S, const Epi& E, const int tid_) {
;     ...
;             PG8_WAIT_V(8); PG8_WAIT_L(0); PG8_BAR; PG8_MMA(1, 0, At, B0); PG8_MMA(1, 1, At, B1); PG8_BAR; PG8_SCHED;
;             PG8_LDB(B0, 1, 0); PG8_LDB(B1, 1, 1); PG8_SCHED; PG8_LDA(At, 1, 0); PG8_STAGE(PG8_SA(0, 1), a2 + hstep, voffA);
;             PG8_WAIT_V(8); PG8_WAIT_L(0); PG8_BAR; PG8_MMA(0, 0, At, B0); PG8_MMA(0, 1, At, B1); PG8_BAR; PG8_SCHED;
	s_setprio 1
	s_waitcnt lgkmcnt(0)
	v_mfma_f32_16x16x32_bf16 v[62:65], v[130:133], v[180:183], v[62:65]
	v_mfma_f32_16x16x32_bf16 v[58:61], v[138:141], v[180:183], v[58:61]
	v_mfma_f32_16x16x32_bf16 v[50:53], v[130:133], v[210:213], v[50:53]
	v_mfma_f32_16x16x32_bf16 v[42:45], v[138:141], v[210:213], v[42:45]
	v_mfma_f32_16x16x32_bf16 v[34:37], v[130:133], v[218:221], v[34:37]
	v_mfma_f32_16x16x32_bf16 v[26:29], v[138:141], v[218:221], v[26:29]
	v_mfma_f32_16x16x32_bf16 v[18:21], v[130:133], v[242:245], v[18:21]
	v_mfma_f32_16x16x32_bf16 v[10:13], v[138:141], v[242:245], v[10:13]
	v_mfma_f32_16x16x32_bf16 v[62:65], v[134:137], v[206:209], v[62:65]
	v_mfma_f32_16x16x32_bf16 v[58:61], v[142:145], v[206:209], v[58:61]
	v_mfma_f32_16x16x32_bf16 v[50:53], v[134:137], v[214:217], v[50:53]
	v_mfma_f32_16x16x32_bf16 v[42:45], v[142:145], v[214:217], v[42:45]
	v_mfma_f32_16x16x32_bf16 v[34:37], v[134:137], v[222:225], v[34:37]
	v_mfma_f32_16x16x32_bf16 v[26:29], v[142:145], v[222:225], v[26:29]
	v_mfma_f32_16x16x32_bf16 v[18:21], v[134:137], v[246:249], v[18:21]
	v_mfma_f32_16x16x32_bf16 v[10:13], v[142:145], v[246:249], v[10:13]
	s_setprio 0
	s_setprio 1
	v_mfma_f32_16x16x32_bf16 v[54:57], v[146:149], v[180:183], v[54:57]
	v_mfma_f32_16x16x32_bf16 v[46:49], v[158:161], v[180:183], v[46:49]
	v_mfma_f32_16x16x32_bf16 v[38:41], v[146:149], v[210:213], v[38:41]
	v_mfma_f32_16x16x32_bf16 v[30:33], v[158:161], v[210:213], v[30:33]
	v_mfma_f32_16x16x32_bf16 v[22:25], v[146:149], v[218:221], v[22:25]
	v_mfma_f32_16x16x32_bf16 v[14:17], v[158:161], v[218:221], v[14:17]
	v_mfma_f32_16x16x32_bf16 v[6:9], v[146:149], v[242:245], v[6:9]
	v_mfma_f32_16x16x32_bf16 v[2:5], v[158:161], v[242:245], v[2:5]
	v_mfma_f32_16x16x32_bf16 v[54:57], v[154:157], v[206:209], v[54:57]
	v_mfma_f32_16x16x32_bf16 v[46:49], v[162:165], v[206:209], v[46:49]
	v_mfma_f32_16x16x32_bf16 v[38:41], v[154:157], v[214:217], v[38:41]
	v_mfma_f32_16x16x32_bf16 v[30:33], v[162:165], v[214:217], v[30:33]
	v_mfma_f32_16x16x32_bf16 v[22:25], v[154:157], v[222:225], v[22:25]
	v_mfma_f32_16x16x32_bf16 v[14:17], v[162:165], v[222:225], v[14:17]
	v_mfma_f32_16x16x32_bf16 v[6:9], v[154:157], v[246:249], v[6:9]
	v_mfma_f32_16x16x32_bf16 v[2:5], v[162:165], v[246:249], v[2:5]
	s_setprio 0
	s_barrier
	s_add_i32 s72, 0, 0x18000
	s_add_i32 s73, 0, 0x1c000
	v_add_u32_e32 v142, s72, v177
	v_add_u32_e32 v162, s73, v177
	ds_read_b128 v[130:133], v142
	ds_read_b128 v[134:137], v142 offset:1024
	ds_read_b128 v[138:141], v142 offset:2048
	ds_read_b128 v[142:145], v142 offset:3072
	ds_read_b128 v[146:149], v162
	ds_read_b128 v[154:157], v162 offset:1024
	ds_read_b128 v[158:161], v162 offset:2048
	ds_read_b128 v[162:165], v162 offset:3072
	s_add_u32 s56, s56, 0x40000
	s_addc_u32 s57, s57, 0
	s_mov_b32 m0, s62
	ds_read_b128 v[180:183], v179 offset:32768
	ds_read_b128 v[206:209], v179 offset:33792
	ds_read_b128 v[210:213], v179 offset:34816
	ds_read_b128 v[214:217], v179 offset:35840
	ds_read_b128 v[218:221], v179 offset:36864
	ds_read_b128 v[222:225], v179 offset:37888
	ds_read_b128 v[242:245], v179 offset:38912
	ds_read_b128 v[246:249], v179 offset:39936
	global_load_lds_dwordx4 v200, s[56:57]
	s_mov_b32 m0, s63
	s_nop 0
	global_load_lds_dwordx4 v202, s[56:57]
	s_waitcnt vmcnt(8)
	s_waitcnt lgkmcnt(0)
	s_barrier
	s_setprio 1
	s_waitcnt lgkmcnt(0)
	v_mfma_f32_16x16x32_bf16 v[126:129], v[130:133], v[180:183], v[126:129]
	v_mfma_f32_16x16x32_bf16 v[122:125], v[138:141], v[180:183], v[122:125]
	v_mfma_f32_16x16x32_bf16 v[118:121], v[130:133], v[210:213], v[118:121]
	v_mfma_f32_16x16x32_bf16 v[114:117], v[138:141], v[210:213], v[114:117]
	v_mfma_f32_16x16x32_bf16 v[98:101], v[130:133], v[218:221], v[98:101]
	v_mfma_f32_16x16x32_bf16 v[90:93], v[138:141], v[218:221], v[90:93]
	v_mfma_f32_16x16x32_bf16 v[82:85], v[130:133], v[242:245], v[82:85]
	v_mfma_f32_16x16x32_bf16 v[74:77], v[138:141], v[242:245], v[74:77]
	v_mfma_f32_16x16x32_bf16 v[126:129], v[134:137], v[206:209], v[126:129]
	v_mfma_f32_16x16x32_bf16 v[122:125], v[142:145], v[206:209], v[122:125]
	v_mfma_f32_16x16x32_bf16 v[118:121], v[134:137], v[214:217], v[118:121]
	v_mfma_f32_16x16x32_bf16 v[114:117], v[142:145], v[214:217], v[114:117]
	v_mfma_f32_16x16x32_bf16 v[98:101], v[134:137], v[222:225], v[98:101]
	v_mfma_f32_16x16x32_bf16 v[90:93], v[142:145], v[222:225], v[90:93]
	v_mfma_f32_16x16x32_bf16 v[82:85], v[134:137], v[246:249], v[82:85]
	v_mfma_f32_16x16x32_bf16 v[74:77], v[142:145], v[246:249], v[74:77]
	s_setprio 0
	s_setprio 1
	v_mfma_f32_16x16x32_bf16 v[110:113], v[146:149], v[180:183], v[110:113]
	v_mfma_f32_16x16x32_bf16 v[106:109], v[158:161], v[180:183], v[106:109]
	v_mfma_f32_16x16x32_bf16 v[102:105], v[146:149], v[210:213], v[102:105]
	v_mfma_f32_16x16x32_bf16 v[94:97], v[158:161], v[210:213], v[94:97]
	v_mfma_f32_16x16x32_bf16 v[86:89], v[146:149], v[218:221], v[86:89]
	v_mfma_f32_16x16x32_bf16 v[78:81], v[158:161], v[218:221], v[78:81]
	v_mfma_f32_16x16x32_bf16 v[70:73], v[146:149], v[242:245], v[70:73]
	v_mfma_f32_16x16x32_bf16 v[66:69], v[158:161], v[242:245], v[66:69]
	v_mfma_f32_16x16x32_bf16 v[110:113], v[154:157], v[206:209], v[110:113]
	v_mfma_f32_16x16x32_bf16 v[106:109], v[162:165], v[206:209], v[106:109]
	v_mfma_f32_16x16x32_bf16 v[102:105], v[154:157], v[214:217], v[102:105]
	v_mfma_f32_16x16x32_bf16 v[94:97], v[162:165], v[214:217], v[94:97]
	v_mfma_f32_16x16x32_bf16 v[86:89], v[154:157], v[222:225], v[86:89]
	v_mfma_f32_16x16x32_bf16 v[78:81], v[162:165], v[222:225], v[78:81]
	v_mfma_f32_16x16x32_bf16 v[70:73], v[154:157], v[246:249], v[70:73]
	v_mfma_f32_16x16x32_bf16 v[66:69], v[162:165], v[246:249], v[66:69]
	s_setprio 0
	s_barrier
; #define PG8_STAGE(bufoff, gbase, voff) do { _Pragma("unroll") for (int _i = 0; _i < 2; ++_i) \
;         __builtin_amdgcn_global_load_lds((const unsigned*)((const char*)(gbase) + (voff)[_i]), (LAS unsigned*)(lds + (bufoff) + ldsw + _i * 8192), 16, 0, 0); } while (0)
; #define PG8_LDA(dst, b, h) do { _Pragma("unroll") for (int m = 0; m < 4; ++m) _Pragma("unroll") for (int k = 0; k < 2; ++k) dst[m][k] = *(const LAS bf16x8*)(lds + PG8_SA(b, h) + aoff + m * 2048 + k * 1024); } while (0)
; #define PG8_MMA(ai, bj, At, Bt) do { __builtin_amdgcn_s_setprio(1); _Pragma("unroll") for (int m = 0; m < 4; ++m) _Pragma("unroll") for (int n = 0; n < 2; ++n) _Pragma("unroll") for (int k = 0; k < 2; ++k) \
;         acc[ai][bj][m][n] = __builtin_amdgcn_mfma_f32_16x16x32_bf16(Bt[n][k], At[m][k], acc[ai][bj][m][n], 0, 0, 0); __builtin_amdgcn_s_setprio(0); } while (0)
; #define PG8_WAIT_V(n) asm volatile("s_waitcnt vmcnt(" #n ")" ::: "memory")
; #define PG8_WAIT_L(n) asm volatile("s_waitcnt lgkmcnt(" #n ")" ::: "memory")
; #define PG8_BAR __builtin_amdgcn_s_barrier()
; #define PG8_SCHED __builtin_amdgcn_sched_barrier(0)
; template <class Epi, class Sched, bool ALIGN_EPI = false, bool SP2 = false>
; __device__ __forceinline__ void gemm_phase(LAS unsigned char* lds, const Gemm g, const Sched& S, const Epi& E, const int tid_) {
;     ...
;             PG8_LDA(At, 1, 1); PG8_STAGE(PG8_SB(1, 0), b3, voffB); PG8_STAGE(PG8_SB(1, 1), b3 + hstep, voffB); PG8_STAGE(PG8_SA(1, 0), a3, voffA);
;             PG8_WAIT_V(8); PG8_WAIT_L(0); PG8_BAR; PG8_MMA(1, 0, At, B0); PG8_MMA(1, 1, At, B1); PG8_BAR; PG8_SCHED;
	s_add_i32 s56, s72, s60
	s_add_i32 m0, s56, 0xffffff80
	ds_read_b128 v[180:183], v179 offset:49152
	ds_read_b128 v[206:209], v179 offset:50176
	ds_read_b128 v[210:213], v179 offset:51200
	ds_read_b128 v[214:217], v179 offset:52224
	ds_read_b128 v[218:221], v179 offset:53248
	ds_read_b128 v[222:225], v179 offset:54272
	ds_read_b128 v[242:245], v179 offset:55296
	ds_read_b128 v[246:249], v179 offset:56320
	global_load_lds_dwordx4 v0, s[54:55] offset:128
	s_add_i32 m0, s56, 0x2000
	s_add_u32 s54, s54, 0x40080
	v_lshl_add_u64 v[184:185], v[236:237], 0, s[96:97]
	s_addc_u32 s55, s55, 0
	s_add_i32 s56, s73, s60
	global_load_lds_dwordx4 v[184:185], off
	s_mov_b32 m0, s56
	s_nop 0
	global_load_lds_dwordx4 v0, s[54:55]
	s_add_i32 m0, s56, 0x2000
	s_nop 0
	global_load_lds_dwordx4 v204, s[54:55]
	v_lshl_add_u64 v[184:185], v[250:251], 0, s[96:97]
	s_mov_b32 m0, s64
	s_nop 0
	global_load_lds_dwordx4 v[184:185], off
	v_lshl_add_u64 v[184:185], v[252:253], 0, s[96:97]
	s_mov_b32 m0, s65
	s_nop 0
	global_load_lds_dwordx4 v[184:185], off
	s_waitcnt vmcnt(8)
	s_waitcnt lgkmcnt(0)
	s_barrier
	s_setprio 1
	s_waitcnt lgkmcnt(0)
	v_mfma_f32_16x16x32_bf16 v[62:65], v[130:133], v[180:183], v[62:65]
	v_mfma_f32_16x16x32_bf16 v[58:61], v[138:141], v[180:183], v[58:61]
	v_mfma_f32_16x16x32_bf16 v[50:53], v[130:133], v[210:213], v[50:53]
	v_mfma_f32_16x16x32_bf16 v[42:45], v[138:141], v[210:213], v[42:45]
	v_mfma_f32_16x16x32_bf16 v[34:37], v[130:133], v[218:221], v[34:37]
	v_mfma_f32_16x16x32_bf16 v[26:29], v[138:141], v[218:221], v[26:29]
	v_mfma_f32_16x16x32_bf16 v[18:21], v[130:133], v[242:245], v[18:21]
	v_mfma_f32_16x16x32_bf16 v[10:13], v[138:141], v[242:245], v[10:13]
	v_mfma_f32_16x16x32_bf16 v[62:65], v[134:137], v[206:209], v[62:65]
	v_mfma_f32_16x16x32_bf16 v[58:61], v[142:145], v[206:209], v[58:61]
	v_mfma_f32_16x16x32_bf16 v[50:53], v[134:137], v[214:217], v[50:53]
	v_mfma_f32_16x16x32_bf16 v[42:45], v[142:145], v[214:217], v[42:45]
	v_mfma_f32_16x16x32_bf16 v[34:37], v[134:137], v[222:225], v[34:37]
	v_mfma_f32_16x16x32_bf16 v[26:29], v[142:145], v[222:225], v[26:29]
	v_mfma_f32_16x16x32_bf16 v[18:21], v[134:137], v[246:249], v[18:21]
	v_mfma_f32_16x16x32_bf16 v[10:13], v[142:145], v[246:249], v[10:13]
	s_setprio 0
	s_setprio 1
	v_mfma_f32_16x16x32_bf16 v[54:57], v[146:149], v[180:183], v[54:57]
	v_mfma_f32_16x16x32_bf16 v[46:49], v[158:161], v[180:183], v[46:49]
	v_mfma_f32_16x16x32_bf16 v[38:41], v[146:149], v[210:213], v[38:41]
	v_mfma_f32_16x16x32_bf16 v[30:33], v[158:161], v[210:213], v[30:33]
	v_mfma_f32_16x16x32_bf16 v[22:25], v[146:149], v[218:221], v[22:25]
	v_mfma_f32_16x16x32_bf16 v[14:17], v[158:161], v[218:221], v[14:17]
	v_mfma_f32_16x16x32_bf16 v[6:9], v[146:149], v[242:245], v[6:9]
	v_mfma_f32_16x16x32_bf16 v[2:5], v[158:161], v[242:245], v[2:5]
	v_mfma_f32_16x16x32_bf16 v[54:57], v[154:157], v[206:209], v[54:57]
	v_mfma_f32_16x16x32_bf16 v[46:49], v[162:165], v[206:209], v[46:49]
	v_mfma_f32_16x16x32_bf16 v[38:41], v[154:157], v[214:217], v[38:41]
	v_mfma_f32_16x16x32_bf16 v[30:33], v[162:165], v[214:217], v[30:33]
	v_mfma_f32_16x16x32_bf16 v[22:25], v[154:157], v[222:225], v[22:25]
	v_mfma_f32_16x16x32_bf16 v[14:17], v[162:165], v[222:225], v[14:17]
	v_mfma_f32_16x16x32_bf16 v[6:9], v[154:157], v[246:249], v[6:9]
	v_mfma_f32_16x16x32_bf16 v[2:5], v[162:165], v[246:249], v[2:5]
	s_setprio 0
	s_barrier
	s_add_i32 s71, s71, 2
	s_add_u32 s50, s50, 0x100
	s_addc_u32 s51, s51, 0
	s_add_u32 s69, s69, 0x100
	s_addc_u32 s70, s70, 0
	s_cmp_gt_u32 s71, 13
	s_cbranch_scc0 .LBB0_96
	s_and_b64 vcc, exec, s[14:15]
	s_cbranch_vccz .LBB0_99
	s_barrier

; #define PG8_STAGE(bufoff, gbase, voff) do { _Pragma("unroll") for (int _i = 0; _i < 2; ++_i) \
;         __builtin_amdgcn_global_load_lds((const unsigned*)((const char*)(gbase) + (voff)[_i]), (LAS unsigned*)(lds + (bufoff) + ldsw + _i * 8192), 16, 0, 0); } while (0)
; #define PG8_LDA(dst, b, h) do { _Pragma("unroll") for (int m = 0; m < 4; ++m) _Pragma("unroll") for (int k = 0; k < 2; ++k) dst[m][k] = *(const LAS bf16x8*)(lds + PG8_SA(b, h) + aoff + m * 2048 + k * 1024); } while (0)
; #define PG8_LDB(dst, b, h) do { _Pragma("unroll") for (int n = 0; n < 2; ++n) _Pragma("unroll") for (int k = 0; k < 2; ++k) dst[n][k] = *(const LAS bf16x8*)(lds + PG8_SB(b, h) + boff + n * 2048 + k * 1024); } while (0)
; #define PG8_MMA(ai, bj, At, Bt) do { __builtin_amdgcn_s_setprio(1); _Pragma("unroll") for (int m = 0; m < 4; ++m) _Pragma("unroll") for (int n = 0; n < 2; ++n) _Pragma("unroll") for (int k = 0; k < 2; ++k) \
;         acc[ai][bj][m][n] = __builtin_amdgcn_mfma_f32_16x16x32_bf16(Bt[n][k], At[m][k], acc[ai][bj][m][n], 0, 0, 0); __builtin_amdgcn_s_setprio(0); } while (0)
; #define PG8_WAIT_V(n) asm volatile("s_waitcnt vmcnt(" #n ")" ::: "memory")
; #define PG8_WAIT_L(n) asm volatile("s_waitcnt lgkmcnt(" #n ")" ::: "memory")
; #define PG8_BAR __builtin_amdgcn_s_barrier()
; #define PG8_SCHED __builtin_amdgcn_sched_barrier(0)
; template <class Epi, class Sched, bool ALIGN_EPI = false, bool SP2 = false>
; __device__ __forceinline__ void gemm_phase(LAS unsigned char* lds, const Gemm g, const Sched& S, const Epi& E, const int tid_) {
;     ...
;             if constexpr (SP2) {
;             PG8_LDB(B0, 0, 0); PG8_LDB(B1, 0, 1); PG8_SCHED; PG8_LDA(At, 0, 0); PG8_STAGE(PG8_SA(1, 1), a1 + hstep, voffA);
;             PG8_WAIT_V(8); PG8_WAIT_L(0); PG8_BAR; PG8_MMA(0, 0, At, B0); PG8_MMA(0, 1, At, B1); PG8_BAR; PG8_SCHED;
;             PG8_LDA(At, 0, 1); PG8_STAGE(PG8_SB(0, 0), b2, voffB); PG8_STAGE(PG8_SB(0, 1), b2 + hstep, voffB); PG8_STAGE(PG8_SA(0, 0), a2, voffA);
;             PG8_WAIT_V(8); PG8_WAIT_L(0); PG8_BAR; PG8_MMA(1, 0, At, B0); PG8_MMA(1, 1, At, B1); PG8_BAR; PG8_SCHED;
.LBB0_120:
	s_add_u32 s50, s48, 0xfffc0080
	s_addc_u32 s51, s49, -1
	s_add_i32 s70, 0, 0x10000
	s_cmp_eq_u32 s69, 12
	s_cselect_b32 s55, s17, s51
	s_cselect_b32 s54, s21, s50
	s_cselect_b32 s51, s15, s68
	s_cselect_b32 s50, s66, s67
	s_add_i32 s72, 0, 0x14000
	v_add_u32_e32 v142, s70, v199
	v_add_u32_e32 v158, s72, v199
	ds_read_b128 v[130:133], v142
	ds_read_b128 v[134:137], v142 offset:1024
	ds_read_b128 v[138:141], v142 offset:2048
	ds_read_b128 v[142:145], v142 offset:3072
	ds_read_b128 v[146:149], v158
	ds_read_b128 v[150:153], v158 offset:1024
	ds_read_b128 v[154:157], v158 offset:2048
	ds_read_b128 v[158:161], v158 offset:3072
	s_add_i32 m0, s47, 0xc000
	ds_read_b128 v[162:165], v237
	ds_read_b128 v[166:169], v237 offset:1024
	ds_read_b128 v[170:173], v237 offset:2048
	ds_read_b128 v[174:177], v237 offset:3072
	ds_read_b128 v[178:181], v237 offset:4096
	ds_read_b128 v[182:185], v237 offset:5120
	ds_read_b128 v[210:213], v237 offset:6144
	ds_read_b128 v[214:217], v237 offset:7168
	global_load_lds_dwordx4 v206, s[48:49]
	s_add_i32 m0, s47, 0xe000
	s_nop 0
	global_load_lds_dwordx4 v208, s[48:49]
	s_waitcnt vmcnt(8)
	s_waitcnt lgkmcnt(0)
	s_barrier
	s_setprio 1
	s_waitcnt lgkmcnt(0)
	v_mfma_f32_16x16x32_bf16 v[126:129], v[130:133], v[162:165], v[126:129]
	v_mfma_f32_16x16x32_bf16 v[122:125], v[138:141], v[162:165], v[122:125]
	v_mfma_f32_16x16x32_bf16 v[110:113], v[130:133], v[170:173], v[110:113]
	v_mfma_f32_16x16x32_bf16 v[106:109], v[138:141], v[170:173], v[106:109]
	v_mfma_f32_16x16x32_bf16 v[94:97], v[130:133], v[178:181], v[94:97]
	v_mfma_f32_16x16x32_bf16 v[90:93], v[138:141], v[178:181], v[90:93]
	v_mfma_f32_16x16x32_bf16 v[78:81], v[130:133], v[210:213], v[78:81]
	v_mfma_f32_16x16x32_bf16 v[74:77], v[138:141], v[210:213], v[74:77]
	v_mfma_f32_16x16x32_bf16 v[126:129], v[134:137], v[166:169], v[126:129]
	v_mfma_f32_16x16x32_bf16 v[122:125], v[142:145], v[166:169], v[122:125]
	v_mfma_f32_16x16x32_bf16 v[110:113], v[134:137], v[174:177], v[110:113]
	v_mfma_f32_16x16x32_bf16 v[106:109], v[142:145], v[174:177], v[106:109]
	v_mfma_f32_16x16x32_bf16 v[94:97], v[134:137], v[182:185], v[94:97]
	v_mfma_f32_16x16x32_bf16 v[90:93], v[142:145], v[182:185], v[90:93]
	v_mfma_f32_16x16x32_bf16 v[78:81], v[134:137], v[214:217], v[78:81]
	v_mfma_f32_16x16x32_bf16 v[74:77], v[142:145], v[214:217], v[74:77]
	s_setprio 0
	s_setprio 1
	v_mfma_f32_16x16x32_bf16 v[118:121], v[146:149], v[162:165], v[118:121]
	v_mfma_f32_16x16x32_bf16 v[114:117], v[154:157], v[162:165], v[114:117]
	v_mfma_f32_16x16x32_bf16 v[102:105], v[146:149], v[170:173], v[102:105]
	v_mfma_f32_16x16x32_bf16 v[98:101], v[154:157], v[170:173], v[98:101]
	v_mfma_f32_16x16x32_bf16 v[86:89], v[146:149], v[178:181], v[86:89]
	v_mfma_f32_16x16x32_bf16 v[82:85], v[154:157], v[178:181], v[82:85]
	v_mfma_f32_16x16x32_bf16 v[70:73], v[146:149], v[210:213], v[70:73]
	v_mfma_f32_16x16x32_bf16 v[66:69], v[154:157], v[210:213], v[66:69]
	v_mfma_f32_16x16x32_bf16 v[118:121], v[150:153], v[166:169], v[118:121]
	v_mfma_f32_16x16x32_bf16 v[114:117], v[158:161], v[166:169], v[114:117]
	v_mfma_f32_16x16x32_bf16 v[102:105], v[150:153], v[174:177], v[102:105]
	v_mfma_f32_16x16x32_bf16 v[98:101], v[158:161], v[174:177], v[98:101]
	v_mfma_f32_16x16x32_bf16 v[86:89], v[150:153], v[182:185], v[86:89]
	v_mfma_f32_16x16x32_bf16 v[82:85], v[158:161], v[182:185], v[82:85]
	v_mfma_f32_16x16x32_bf16 v[70:73], v[150:153], v[214:217], v[70:73]
	v_mfma_f32_16x16x32_bf16 v[66:69], v[158:161], v[214:217], v[66:69]
	s_setprio 0
	s_barrier
	s_add_i32 s70, s70, s58
	s_mov_b32 m0, s70
	ds_read_b128 v[162:165], v237 offset:16384
	ds_read_b128 v[166:169], v237 offset:17408
	ds_read_b128 v[170:173], v237 offset:18432
	ds_read_b128 v[174:177], v237 offset:19456
	ds_read_b128 v[178:181], v237 offset:20480
	ds_read_b128 v[182:185], v237 offset:21504
	ds_read_b128 v[210:213], v237 offset:22528
	ds_read_b128 v[214:217], v237 offset:23552
	global_load_lds_dwordx4 v0, s[50:51]
	s_add_i32 m0, s70, 0x2000
	s_add_u32 s70, s50, 0x40000
	v_lshl_add_u64 v[218:219], s[50:51], 0, v[204:205]
	s_addc_u32 s71, s51, 0
	s_add_i32 s72, s72, s58
	global_load_lds_dwordx4 v204, s[50:51]
	s_mov_b32 m0, s72
	v_lshl_add_u64 v[222:223], s[54:55], 0, v[202:203]
	global_load_lds_dwordx4 v0, s[70:71]
	s_add_i32 m0, s72, 0x2000
	s_nop 0
	global_load_lds_dwordx4 v204, s[70:71]
	v_lshl_add_u64 v[220:221], s[54:55], 0, v[200:201]
	s_mov_b32 m0, s47
	s_nop 0
	global_load_lds_dwordx4 v200, s[54:55]
	s_mov_b32 m0, s59
	s_nop 0
	global_load_lds_dwordx4 v202, s[54:55]
	s_waitcnt vmcnt(8)
	s_waitcnt lgkmcnt(0)
	s_barrier
; #define PG8_STAGE(bufoff, gbase, voff) do { _Pragma("unroll") for (int _i = 0; _i < 2; ++_i) \
;         __builtin_amdgcn_global_load_lds((const unsigned*)((const char*)(gbase) + (voff)[_i]), (LAS unsigned*)(lds + (bufoff) + ldsw + _i * 8192), 16, 0, 0); } while (0)
; #define PG8_LDA(dst, b, h) do { _Pragma("unroll") for (int m = 0; m < 4; ++m) _Pragma("unroll") for (int k = 0; k < 2; ++k) dst[m][k] = *(const LAS bf16x8*)(lds + PG8_SA(b, h) + aoff + m * 2048 + k * 1024); } while (0)
; #define PG8_LDB(dst, b, h) do { _Pragma("unroll") for (int n = 0; n < 2; ++n) _Pragma("unroll") for (int k = 0; k < 2; ++k) dst[n][k] = *(const LAS bf16x8*)(lds + PG8_SB(b, h) + boff + n * 2048 + k * 1024); } while (0)
; #define PG8_MMA(ai, bj, At, Bt) do { __builtin_amdgcn_s_setprio(1); _Pragma("unroll") for (int m = 0; m < 4; ++m) _Pragma("unroll") for (int n = 0; n < 2; ++n) _Pragma("unroll") for (int k = 0; k < 2; ++k) \
;         acc[ai][bj][m][n] = __builtin_amdgcn_mfma_f32_16x16x32_bf16(Bt[n][k], At[m][k], acc[ai][bj][m][n], 0, 0, 0); __builtin_amdgcn_s_setprio(0); } while (0)
; #define PG8_WAIT_V(n) asm volatile("s_waitcnt vmcnt(" #n ")" ::: "memory")
; #define PG8_WAIT_L(n) asm volatile("s_waitcnt lgkmcnt(" #n ")" ::: "memory")
; #define PG8_BAR __builtin_amdgcn_s_barrier()
; #define PG8_SCHED __builtin_amdgcn_sched_barrier(0)
; template <class Epi, class Sched, bool ALIGN_EPI = false, bool SP2 = false>
; __device__ __forceinline__ void gemm_phase(LAS unsigned char* lds, const Gemm g, const Sched& S, const Epi& E, const int tid_) {
;     ...
;             PG8_WAIT_V(8); PG8_WAIT_L(0); PG8_BAR; PG8_MMA(1, 0, At, B0); PG8_MMA(1, 1, At, B1); PG8_BAR; PG8_SCHED;
;             PG8_LDB(B0, 1, 0); PG8_LDB(B1, 1, 1); PG8_SCHED; PG8_LDA(At, 1, 0); PG8_STAGE(PG8_SA(0, 1), a2 + hstep, voffA);
;             PG8_WAIT_V(8); PG8_WAIT_L(0); PG8_BAR; PG8_MMA(0, 0, At, B0); PG8_MMA(0, 1, At, B1); PG8_BAR; PG8_SCHED;
	s_setprio 1
	s_waitcnt lgkmcnt(0)
	v_mfma_f32_16x16x32_bf16 v[62:65], v[130:133], v[162:165], v[62:65]
	v_mfma_f32_16x16x32_bf16 v[58:61], v[138:141], v[162:165], v[58:61]
	v_mfma_f32_16x16x32_bf16 v[46:49], v[130:133], v[170:173], v[46:49]
	v_mfma_f32_16x16x32_bf16 v[42:45], v[138:141], v[170:173], v[42:45]
	v_mfma_f32_16x16x32_bf16 v[30:33], v[130:133], v[178:181], v[30:33]
	v_mfma_f32_16x16x32_bf16 v[26:29], v[138:141], v[178:181], v[26:29]
	v_mfma_f32_16x16x32_bf16 v[14:17], v[130:133], v[210:213], v[14:17]
	v_mfma_f32_16x16x32_bf16 v[10:13], v[138:141], v[210:213], v[10:13]
	v_mfma_f32_16x16x32_bf16 v[62:65], v[134:137], v[166:169], v[62:65]
	v_mfma_f32_16x16x32_bf16 v[58:61], v[142:145], v[166:169], v[58:61]
	v_mfma_f32_16x16x32_bf16 v[46:49], v[134:137], v[174:177], v[46:49]
	v_mfma_f32_16x16x32_bf16 v[42:45], v[142:145], v[174:177], v[42:45]
	v_mfma_f32_16x16x32_bf16 v[30:33], v[134:137], v[182:185], v[30:33]
	v_mfma_f32_16x16x32_bf16 v[26:29], v[142:145], v[182:185], v[26:29]
	v_mfma_f32_16x16x32_bf16 v[14:17], v[134:137], v[214:217], v[14:17]
	v_mfma_f32_16x16x32_bf16 v[10:13], v[142:145], v[214:217], v[10:13]
	s_setprio 0
	s_setprio 1
	v_mfma_f32_16x16x32_bf16 v[54:57], v[146:149], v[162:165], v[54:57]
	v_mfma_f32_16x16x32_bf16 v[50:53], v[154:157], v[162:165], v[50:53]
	v_mfma_f32_16x16x32_bf16 v[38:41], v[146:149], v[170:173], v[38:41]
	v_mfma_f32_16x16x32_bf16 v[34:37], v[154:157], v[170:173], v[34:37]
	v_mfma_f32_16x16x32_bf16 v[22:25], v[146:149], v[178:181], v[22:25]
	v_mfma_f32_16x16x32_bf16 v[18:21], v[154:157], v[178:181], v[18:21]
	v_mfma_f32_16x16x32_bf16 v[6:9], v[146:149], v[210:213], v[6:9]
	v_mfma_f32_16x16x32_bf16 v[2:5], v[154:157], v[210:213], v[2:5]
	v_mfma_f32_16x16x32_bf16 v[54:57], v[150:153], v[166:169], v[54:57]
	v_mfma_f32_16x16x32_bf16 v[50:53], v[158:161], v[166:169], v[50:53]
	v_mfma_f32_16x16x32_bf16 v[38:41], v[150:153], v[174:177], v[38:41]
	v_mfma_f32_16x16x32_bf16 v[34:37], v[158:161], v[174:177], v[34:37]
	v_mfma_f32_16x16x32_bf16 v[22:25], v[150:153], v[182:185], v[22:25]
	v_mfma_f32_16x16x32_bf16 v[18:21], v[158:161], v[182:185], v[18:21]
	v_mfma_f32_16x16x32_bf16 v[6:9], v[150:153], v[214:217], v[6:9]
	v_mfma_f32_16x16x32_bf16 v[2:5], v[158:161], v[214:217], v[2:5]
	s_setprio 0
	s_barrier
	s_add_i32 s70, 0, 0x18000
	s_add_i32 s71, 0, 0x1c000
	v_add_u32_e32 v142, s70, v199
	v_add_u32_e32 v158, s71, v199
	ds_read_b128 v[130:133], v142
	ds_read_b128 v[134:137], v142 offset:1024
	ds_read_b128 v[138:141], v142 offset:2048
	ds_read_b128 v[142:145], v142 offset:3072
	ds_read_b128 v[146:149], v158
	ds_read_b128 v[150:153], v158 offset:1024
	ds_read_b128 v[154:157], v158 offset:2048
	ds_read_b128 v[158:161], v158 offset:3072
	s_add_u32 s54, s54, 0x40000
	s_addc_u32 s55, s55, 0
	s_mov_b32 m0, s60
	ds_read_b128 v[162:165], v237 offset:32768
	ds_read_b128 v[166:169], v237 offset:33792
	ds_read_b128 v[170:173], v237 offset:34816
	ds_read_b128 v[174:177], v237 offset:35840
	ds_read_b128 v[178:181], v237 offset:36864
	ds_read_b128 v[182:185], v237 offset:37888
	ds_read_b128 v[210:213], v237 offset:38912
	ds_read_b128 v[214:217], v237 offset:39936
	global_load_lds_dwordx4 v200, s[54:55]
	s_mov_b32 m0, s61
	s_nop 0
	global_load_lds_dwordx4 v202, s[54:55]
	s_waitcnt vmcnt(8)
	s_waitcnt lgkmcnt(0)
	s_barrier
	s_setprio 1
	s_waitcnt lgkmcnt(0)
	v_mfma_f32_16x16x32_bf16 v[126:129], v[130:133], v[162:165], v[126:129]
	v_mfma_f32_16x16x32_bf16 v[122:125], v[138:141], v[162:165], v[122:125]
	v_mfma_f32_16x16x32_bf16 v[110:113], v[130:133], v[170:173], v[110:113]
	v_mfma_f32_16x16x32_bf16 v[106:109], v[138:141], v[170:173], v[106:109]
	v_mfma_f32_16x16x32_bf16 v[94:97], v[130:133], v[178:181], v[94:97]
	v_mfma_f32_16x16x32_bf16 v[90:93], v[138:141], v[178:181], v[90:93]
	v_mfma_f32_16x16x32_bf16 v[78:81], v[130:133], v[210:213], v[78:81]
	v_mfma_f32_16x16x32_bf16 v[74:77], v[138:141], v[210:213], v[74:77]
	v_mfma_f32_16x16x32_bf16 v[126:129], v[134:137], v[166:169], v[126:129]
	v_mfma_f32_16x16x32_bf16 v[122:125], v[142:145], v[166:169], v[122:125]
	v_mfma_f32_16x16x32_bf16 v[110:113], v[134:137], v[174:177], v[110:113]
	v_mfma_f32_16x16x32_bf16 v[106:109], v[142:145], v[174:177], v[106:109]
	v_mfma_f32_16x16x32_bf16 v[94:97], v[134:137], v[182:185], v[94:97]
	v_mfma_f32_16x16x32_bf16 v[90:93], v[142:145], v[182:185], v[90:93]
	v_mfma_f32_16x16x32_bf16 v[78:81], v[134:137], v[214:217], v[78:81]
	v_mfma_f32_16x16x32_bf16 v[74:77], v[142:145], v[214:217], v[74:77]
	s_setprio 0
	s_setprio 1
	v_mfma_f32_16x16x32_bf16 v[118:121], v[146:149], v[162:165], v[118:121]
	v_mfma_f32_16x16x32_bf16 v[114:117], v[154:157], v[162:165], v[114:117]
	v_mfma_f32_16x16x32_bf16 v[102:105], v[146:149], v[170:173], v[102:105]
	v_mfma_f32_16x16x32_bf16 v[98:101], v[154:157], v[170:173], v[98:101]
	v_mfma_f32_16x16x32_bf16 v[86:89], v[146:149], v[178:181], v[86:89]
	v_mfma_f32_16x16x32_bf16 v[82:85], v[154:157], v[178:181], v[82:85]
	v_mfma_f32_16x16x32_bf16 v[70:73], v[146:149], v[210:213], v[70:73]
	v_mfma_f32_16x16x32_bf16 v[66:69], v[154:157], v[210:213], v[66:69]
	v_mfma_f32_16x16x32_bf16 v[118:121], v[150:153], v[166:169], v[118:121]
	v_mfma_f32_16x16x32_bf16 v[114:117], v[158:161], v[166:169], v[114:117]
	v_mfma_f32_16x16x32_bf16 v[102:105], v[150:153], v[174:177], v[102:105]
	v_mfma_f32_16x16x32_bf16 v[98:101], v[158:161], v[174:177], v[98:101]
	v_mfma_f32_16x16x32_bf16 v[86:89], v[150:153], v[182:185], v[86:89]
	v_mfma_f32_16x16x32_bf16 v[82:85], v[158:161], v[182:185], v[82:85]
	v_mfma_f32_16x16x32_bf16 v[70:73], v[150:153], v[214:217], v[70:73]
	v_mfma_f32_16x16x32_bf16 v[66:69], v[158:161], v[214:217], v[66:69]
	s_setprio 0
	s_barrier
; #define PG8_STAGE(bufoff, gbase, voff) do { _Pragma("unroll") for (int _i = 0; _i < 2; ++_i) \
;         __builtin_amdgcn_global_load_lds((const unsigned*)((const char*)(gbase) + (voff)[_i]), (LAS unsigned*)(lds + (bufoff) + ldsw + _i * 8192), 16, 0, 0); } while (0)
; #define PG8_LDA(dst, b, h) do { _Pragma("unroll") for (int m = 0; m < 4; ++m) _Pragma("unroll") for (int k = 0; k < 2; ++k) dst[m][k] = *(const LAS bf16x8*)(lds + PG8_SA(b, h) + aoff + m * 2048 + k * 1024); } while (0)
; #define PG8_MMA(ai, bj, At, Bt) do { __builtin_amdgcn_s_setprio(1); _Pragma("unroll") for (int m = 0; m < 4; ++m) _Pragma("unroll") for (int n = 0; n < 2; ++n) _Pragma("unroll") for (int k = 0; k < 2; ++k) \
;         acc[ai][bj][m][n] = __builtin_amdgcn_mfma_f32_16x16x32_bf16(Bt[n][k], At[m][k], acc[ai][bj][m][n], 0, 0, 0); __builtin_amdgcn_s_setprio(0); } while (0)
; #define PG8_WAIT_V(n) asm volatile("s_waitcnt vmcnt(" #n ")" ::: "memory")
; #define PG8_WAIT_L(n) asm volatile("s_waitcnt lgkmcnt(" #n ")" ::: "memory")
; #define PG8_BAR __builtin_amdgcn_s_barrier()
; #define PG8_SCHED __builtin_amdgcn_sched_barrier(0)
; template <class Epi, class Sched, bool ALIGN_EPI = false, bool SP2 = false>
; __device__ __forceinline__ void gemm_phase(LAS unsigned char* lds, const Gemm g, const Sched& S, const Epi& E, const int tid_) {
;     ...
;             PG8_LDA(At, 1, 1); PG8_STAGE(PG8_SB(1, 0), b3, voffB); PG8_STAGE(PG8_SB(1, 1), b3 + hstep, voffB); PG8_STAGE(PG8_SA(1, 0), a3, voffA);
;             PG8_WAIT_V(8); PG8_WAIT_L(0); PG8_BAR; PG8_MMA(1, 0, At, B0); PG8_MMA(1, 1, At, B1); PG8_BAR; PG8_SCHED;
	s_add_i32 s54, s70, s58
	s_add_i32 m0, s54, 0xffffff80
	ds_read_b128 v[162:165], v237 offset:49152
	ds_read_b128 v[166:169], v237 offset:50176
	ds_read_b128 v[170:173], v237 offset:51200
	ds_read_b128 v[174:177], v237 offset:52224
	ds_read_b128 v[178:181], v237 offset:53248
	ds_read_b128 v[182:185], v237 offset:54272
	ds_read_b128 v[210:213], v237 offset:55296
	ds_read_b128 v[214:217], v237 offset:56320
	global_load_lds_dwordx4 v0, s[50:51] offset:128
	s_add_i32 m0, s54, 0x2000
	s_add_u32 s50, s50, 0x40080
	v_lshl_add_u64 v[192:193], v[218:219], 0, s[96:97]
	s_addc_u32 s51, s51, 0
	s_add_i32 s54, s71, s58
	global_load_lds_dwordx4 v[192:193], off
	s_mov_b32 m0, s54
	s_nop 0
	global_load_lds_dwordx4 v0, s[50:51]
	s_add_i32 m0, s54, 0x2000
	s_nop 0
	global_load_lds_dwordx4 v204, s[50:51]
	v_lshl_add_u64 v[192:193], v[220:221], 0, s[96:97]
	s_mov_b32 m0, s62
	s_nop 0
	global_load_lds_dwordx4 v[192:193], off
	v_lshl_add_u64 v[192:193], v[222:223], 0, s[96:97]
	s_mov_b32 m0, s63
	s_nop 0
	global_load_lds_dwordx4 v[192:193], off
	s_waitcnt vmcnt(8)
	s_waitcnt lgkmcnt(0)
	s_barrier
	s_setprio 1
	s_waitcnt lgkmcnt(0)
	v_mfma_f32_16x16x32_bf16 v[62:65], v[130:133], v[162:165], v[62:65]
	v_mfma_f32_16x16x32_bf16 v[58:61], v[138:141], v[162:165], v[58:61]
	v_mfma_f32_16x16x32_bf16 v[46:49], v[130:133], v[170:173], v[46:49]
	v_mfma_f32_16x16x32_bf16 v[42:45], v[138:141], v[170:173], v[42:45]
	v_mfma_f32_16x16x32_bf16 v[30:33], v[130:133], v[178:181], v[30:33]
	v_mfma_f32_16x16x32_bf16 v[26:29], v[138:141], v[178:181], v[26:29]
	v_mfma_f32_16x16x32_bf16 v[14:17], v[130:133], v[210:213], v[14:17]
	v_mfma_f32_16x16x32_bf16 v[10:13], v[138:141], v[210:213], v[10:13]
	v_mfma_f32_16x16x32_bf16 v[62:65], v[134:137], v[166:169], v[62:65]
	v_mfma_f32_16x16x32_bf16 v[58:61], v[142:145], v[166:169], v[58:61]
	v_mfma_f32_16x16x32_bf16 v[46:49], v[134:137], v[174:177], v[46:49]
	v_mfma_f32_16x16x32_bf16 v[42:45], v[142:145], v[174:177], v[42:45]
	v_mfma_f32_16x16x32_bf16 v[30:33], v[134:137], v[182:185], v[30:33]
	v_mfma_f32_16x16x32_bf16 v[26:29], v[142:145], v[182:185], v[26:29]
	v_mfma_f32_16x16x32_bf16 v[14:17], v[134:137], v[214:217], v[14:17]
	v_mfma_f32_16x16x32_bf16 v[10:13], v[142:145], v[214:217], v[10:13]
	s_setprio 0
	s_setprio 1
	v_mfma_f32_16x16x32_bf16 v[54:57], v[146:149], v[162:165], v[54:57]
	v_mfma_f32_16x16x32_bf16 v[50:53], v[154:157], v[162:165], v[50:53]
	v_mfma_f32_16x16x32_bf16 v[38:41], v[146:149], v[170:173], v[38:41]
	v_mfma_f32_16x16x32_bf16 v[34:37], v[154:157], v[170:173], v[34:37]
	v_mfma_f32_16x16x32_bf16 v[22:25], v[146:149], v[178:181], v[22:25]
	v_mfma_f32_16x16x32_bf16 v[18:21], v[154:157], v[178:181], v[18:21]
	v_mfma_f32_16x16x32_bf16 v[6:9], v[146:149], v[210:213], v[6:9]
	v_mfma_f32_16x16x32_bf16 v[2:5], v[154:157], v[210:213], v[2:5]
	v_mfma_f32_16x16x32_bf16 v[54:57], v[150:153], v[166:169], v[54:57]
	v_mfma_f32_16x16x32_bf16 v[50:53], v[158:161], v[166:169], v[50:53]
	v_mfma_f32_16x16x32_bf16 v[38:41], v[150:153], v[174:177], v[38:41]
	v_mfma_f32_16x16x32_bf16 v[34:37], v[158:161], v[174:177], v[34:37]
	v_mfma_f32_16x16x32_bf16 v[22:25], v[150:153], v[182:185], v[22:25]
	v_mfma_f32_16x16x32_bf16 v[18:21], v[158:161], v[182:185], v[18:21]
	v_mfma_f32_16x16x32_bf16 v[6:9], v[150:153], v[214:217], v[6:9]
	v_mfma_f32_16x16x32_bf16 v[2:5], v[158:161], v[214:217], v[2:5]
	s_setprio 0
	s_barrier
	s_add_i32 s69, s69, 2
	s_add_u32 s48, s48, 0x100
	s_addc_u32 s49, s49, 0
	s_add_u32 s67, s67, 0x100
	s_addc_u32 s68, s68, 0
	s_cmp_gt_u32 s69, 13
	s_cbranch_scc0 .LBB0_120
	s_and_b64 vcc, exec, s[12:13]
	s_cbranch_vccz .LBB0_123
	s_barrier

; #define PG8_STAGE(bufoff, gbase, voff) do { _Pragma("unroll") for (int _i = 0; _i < 2; ++_i) \
;         __builtin_amdgcn_global_load_lds((const unsigned*)((const char*)(gbase) + (voff)[_i]), (LAS unsigned*)(lds + (bufoff) + ldsw + _i * 8192), 16, 0, 0); } while (0)
; #define PG8_LDA(dst, b, h) do { _Pragma("unroll") for (int m = 0; m < 4; ++m) _Pragma("unroll") for (int k = 0; k < 2; ++k) dst[m][k] = *(const LAS bf16x8*)(lds + PG8_SA(b, h) + aoff + m * 2048 + k * 1024); } while (0)
; #define PG8_LDB(dst, b, h) do { _Pragma("unroll") for (int n = 0; n < 2; ++n) _Pragma("unroll") for (int k = 0; k < 2; ++k) dst[n][k] = *(const LAS bf16x8*)(lds + PG8_SB(b, h) + boff + n * 2048 + k * 1024); } while (0)
; #define PG8_MMA(ai, bj, At, Bt) do { __builtin_amdgcn_s_setprio(1); _Pragma("unroll") for (int m = 0; m < 4; ++m) _Pragma("unroll") for (int n = 0; n < 2; ++n) _Pragma("unroll") for (int k = 0; k < 2; ++k) \
;         acc[ai][bj][m][n] = __builtin_amdgcn_mfma_f32_16x16x32_bf16(Bt[n][k], At[m][k], acc[ai][bj][m][n], 0, 0, 0); __builtin_amdgcn_s_setprio(0); } while (0)
; #define PG8_WAIT_V(n) asm volatile("s_waitcnt vmcnt(" #n ")" ::: "memory")
; #define PG8_WAIT_L(n) asm volatile("s_waitcnt lgkmcnt(" #n ")" ::: "memory")
; #define PG8_BAR __builtin_amdgcn_s_barrier()
; #define PG8_SCHED __builtin_amdgcn_sched_barrier(0)
; template <class Epi, class Sched, bool ALIGN_EPI = false, bool SP2 = false>
; __device__ __forceinline__ void gemm_phase(LAS unsigned char* lds, const Gemm g, const Sched& S, const Epi& E, const int tid_) {
;     ...
;             if constexpr (SP2) {
;             PG8_LDB(B0, 0, 0); PG8_LDB(B1, 0, 1); PG8_SCHED; PG8_LDA(At, 0, 0); PG8_STAGE(PG8_SA(1, 1), a1 + hstep, voffA);
;             PG8_WAIT_V(8); PG8_WAIT_L(0); PG8_BAR; PG8_MMA(0, 0, At, B0); PG8_MMA(0, 1, At, B1); PG8_BAR; PG8_SCHED;
;             PG8_LDA(At, 0, 1); PG8_STAGE(PG8_SB(0, 0), b2, voffB); PG8_STAGE(PG8_SB(0, 1), b2 + hstep, voffB); PG8_STAGE(PG8_SA(0, 0), a2, voffA);
;             PG8_WAIT_V(8); PG8_WAIT_L(0); PG8_BAR; PG8_MMA(1, 0, At, B0); PG8_MMA(1, 1, At, B1); PG8_BAR; PG8_SCHED;
.LBB0_253:
	s_add_u32 s58, s54, 0xfff80080
	s_addc_u32 s59, s55, -1
	s_add_i32 s74, 0, 0x10000
	s_cmp_eq_u32 s73, 28
	s_cselect_b32 s61, s20, s59
	s_cselect_b32 s60, s21, s58
	s_cselect_b32 s59, s43, s72
	s_cselect_b32 s58, s47, s49
	s_add_i32 s76, 0, 0x14000
	v_add_u32_e32 v156, s74, v145
	v_add_u32_e32 v172, s76, v145
	ds_read_b128 v[140:143], v156
	ds_read_b128 v[148:151], v156 offset:1024
	ds_read_b128 v[152:155], v156 offset:2048
	ds_read_b128 v[156:159], v156 offset:3072
	ds_read_b128 v[160:163], v172
	ds_read_b128 v[164:167], v172 offset:1024
	ds_read_b128 v[168:171], v172 offset:2048
	ds_read_b128 v[172:175], v172 offset:3072
	s_add_i32 m0, s57, 0xc000
	ds_read_b128 v[176:179], v147
	ds_read_b128 v[180:183], v147 offset:1024
	ds_read_b128 v[200:203], v147 offset:2048
	ds_read_b128 v[204:207], v147 offset:3072
	ds_read_b128 v[208:211], v147 offset:4096
	ds_read_b128 v[212:215], v147 offset:5120
	ds_read_b128 v[216:219], v147 offset:6144
	ds_read_b128 v[220:223], v147 offset:7168
	global_load_lds_dwordx4 v136, s[54:55]
	s_add_i32 m0, s57, 0xe000
	s_nop 0
	global_load_lds_dwordx4 v138, s[54:55]
	s_waitcnt vmcnt(8)
	s_waitcnt lgkmcnt(0)
	s_barrier
	s_setprio 1
	s_waitcnt lgkmcnt(0)
	v_mfma_f32_16x16x32_bf16 v[126:129], v[140:143], v[176:179], v[126:129]
	v_mfma_f32_16x16x32_bf16 v[122:125], v[152:155], v[176:179], v[122:125]
	v_mfma_f32_16x16x32_bf16 v[110:113], v[140:143], v[200:203], v[110:113]
	v_mfma_f32_16x16x32_bf16 v[106:109], v[152:155], v[200:203], v[106:109]
	v_mfma_f32_16x16x32_bf16 v[94:97], v[140:143], v[208:211], v[94:97]
	v_mfma_f32_16x16x32_bf16 v[90:93], v[152:155], v[208:211], v[90:93]
	v_mfma_f32_16x16x32_bf16 v[78:81], v[140:143], v[216:219], v[78:81]
	v_mfma_f32_16x16x32_bf16 v[74:77], v[152:155], v[216:219], v[74:77]
	v_mfma_f32_16x16x32_bf16 v[126:129], v[148:151], v[180:183], v[126:129]
	v_mfma_f32_16x16x32_bf16 v[122:125], v[156:159], v[180:183], v[122:125]
	v_mfma_f32_16x16x32_bf16 v[110:113], v[148:151], v[204:207], v[110:113]
	v_mfma_f32_16x16x32_bf16 v[106:109], v[156:159], v[204:207], v[106:109]
	v_mfma_f32_16x16x32_bf16 v[94:97], v[148:151], v[212:215], v[94:97]
	v_mfma_f32_16x16x32_bf16 v[90:93], v[156:159], v[212:215], v[90:93]
	v_mfma_f32_16x16x32_bf16 v[78:81], v[148:151], v[220:223], v[78:81]
	v_mfma_f32_16x16x32_bf16 v[74:77], v[156:159], v[220:223], v[74:77]
	s_setprio 0
	s_setprio 1
	v_mfma_f32_16x16x32_bf16 v[118:121], v[160:163], v[176:179], v[118:121]
	v_mfma_f32_16x16x32_bf16 v[114:117], v[168:171], v[176:179], v[114:117]
	v_mfma_f32_16x16x32_bf16 v[102:105], v[160:163], v[200:203], v[102:105]
	v_mfma_f32_16x16x32_bf16 v[98:101], v[168:171], v[200:203], v[98:101]
	v_mfma_f32_16x16x32_bf16 v[86:89], v[160:163], v[208:211], v[86:89]
	v_mfma_f32_16x16x32_bf16 v[82:85], v[168:171], v[208:211], v[82:85]
	v_mfma_f32_16x16x32_bf16 v[70:73], v[160:163], v[216:219], v[70:73]
	v_mfma_f32_16x16x32_bf16 v[66:69], v[168:171], v[216:219], v[66:69]
	v_mfma_f32_16x16x32_bf16 v[118:121], v[164:167], v[180:183], v[118:121]
	v_mfma_f32_16x16x32_bf16 v[114:117], v[172:175], v[180:183], v[114:117]
	v_mfma_f32_16x16x32_bf16 v[102:105], v[164:167], v[204:207], v[102:105]
	v_mfma_f32_16x16x32_bf16 v[98:101], v[172:175], v[204:207], v[98:101]
	v_mfma_f32_16x16x32_bf16 v[86:89], v[164:167], v[212:215], v[86:89]
	v_mfma_f32_16x16x32_bf16 v[82:85], v[172:175], v[212:215], v[82:85]
	v_mfma_f32_16x16x32_bf16 v[70:73], v[164:167], v[220:223], v[70:73]
	v_mfma_f32_16x16x32_bf16 v[66:69], v[172:175], v[220:223], v[66:69]
	s_setprio 0
	s_barrier
	s_add_i32 s74, s74, s62
	s_mov_b32 m0, s74
	ds_read_b128 v[176:179], v147 offset:16384
	ds_read_b128 v[180:183], v147 offset:17408
	ds_read_b128 v[200:203], v147 offset:18432
	ds_read_b128 v[204:207], v147 offset:19456
	ds_read_b128 v[208:211], v147 offset:20480
	ds_read_b128 v[212:215], v147 offset:21504
	ds_read_b128 v[216:219], v147 offset:22528
	ds_read_b128 v[220:223], v147 offset:23552
	global_load_lds_dwordx4 v0, s[58:59]
	s_add_i32 m0, s74, 0x2000
	s_add_u32 s74, s58, 0x80000
	v_lshl_add_u64 v[224:225], s[58:59], 0, v[134:135]
	s_addc_u32 s75, s59, 0
	s_add_i32 s76, s76, s62
	global_load_lds_dwordx4 v134, s[58:59]
	s_mov_b32 m0, s76
	v_lshl_add_u64 v[242:243], s[60:61], 0, v[132:133]
	global_load_lds_dwordx4 v0, s[74:75]
	s_add_i32 m0, s76, 0x2000
	s_nop 0
	global_load_lds_dwordx4 v134, s[74:75]
	v_lshl_add_u64 v[236:237], s[60:61], 0, v[130:131]
	s_mov_b32 m0, s57
	s_nop 0
	global_load_lds_dwordx4 v130, s[60:61]
	s_mov_b32 m0, s63
	s_nop 0
	global_load_lds_dwordx4 v132, s[60:61]
	s_waitcnt vmcnt(8)
	s_waitcnt lgkmcnt(0)
	s_barrier
; #define PG8_STAGE(bufoff, gbase, voff) do { _Pragma("unroll") for (int _i = 0; _i < 2; ++_i) \
;         __builtin_amdgcn_global_load_lds((const unsigned*)((const char*)(gbase) + (voff)[_i]), (LAS unsigned*)(lds + (bufoff) + ldsw + _i * 8192), 16, 0, 0); } while (0)
; #define PG8_LDA(dst, b, h) do { _Pragma("unroll") for (int m = 0; m < 4; ++m) _Pragma("unroll") for (int k = 0; k < 2; ++k) dst[m][k] = *(const LAS bf16x8*)(lds + PG8_SA(b, h) + aoff + m * 2048 + k * 1024); } while (0)
; #define PG8_LDB(dst, b, h) do { _Pragma("unroll") for (int n = 0; n < 2; ++n) _Pragma("unroll") for (int k = 0; k < 2; ++k) dst[n][k] = *(const LAS bf16x8*)(lds + PG8_SB(b, h) + boff + n * 2048 + k * 1024); } while (0)
; #define PG8_MMA(ai, bj, At, Bt) do { __builtin_amdgcn_s_setprio(1); _Pragma("unroll") for (int m = 0; m < 4; ++m) _Pragma("unroll") for (int n = 0; n < 2; ++n) _Pragma("unroll") for (int k = 0; k < 2; ++k) \
;         acc[ai][bj][m][n] = __builtin_amdgcn_mfma_f32_16x16x32_bf16(Bt[n][k], At[m][k], acc[ai][bj][m][n], 0, 0, 0); __builtin_amdgcn_s_setprio(0); } while (0)
; #define PG8_WAIT_V(n) asm volatile("s_waitcnt vmcnt(" #n ")" ::: "memory")
; #define PG8_WAIT_L(n) asm volatile("s_waitcnt lgkmcnt(" #n ")" ::: "memory")
; #define PG8_BAR __builtin_amdgcn_s_barrier()
; #define PG8_SCHED __builtin_amdgcn_sched_barrier(0)
; template <class Epi, class Sched, bool ALIGN_EPI = false, bool SP2 = false>
; __device__ __forceinline__ void gemm_phase(LAS unsigned char* lds, const Gemm g, const Sched& S, const Epi& E, const int tid_) {
;     ...
;             PG8_WAIT_V(8); PG8_WAIT_L(0); PG8_BAR; PG8_MMA(1, 0, At, B0); PG8_MMA(1, 1, At, B1); PG8_BAR; PG8_SCHED;
;             PG8_LDB(B0, 1, 0); PG8_LDB(B1, 1, 1); PG8_SCHED; PG8_LDA(At, 1, 0); PG8_STAGE(PG8_SA(0, 1), a2 + hstep, voffA);
;             PG8_WAIT_V(8); PG8_WAIT_L(0); PG8_BAR; PG8_MMA(0, 0, At, B0); PG8_MMA(0, 1, At, B1); PG8_BAR; PG8_SCHED;
	s_setprio 1
	s_waitcnt lgkmcnt(0)
	v_mfma_f32_16x16x32_bf16 v[62:65], v[140:143], v[176:179], v[62:65]
	v_mfma_f32_16x16x32_bf16 v[58:61], v[152:155], v[176:179], v[58:61]
	v_mfma_f32_16x16x32_bf16 v[46:49], v[140:143], v[200:203], v[46:49]
	v_mfma_f32_16x16x32_bf16 v[42:45], v[152:155], v[200:203], v[42:45]
	v_mfma_f32_16x16x32_bf16 v[30:33], v[140:143], v[208:211], v[30:33]
	v_mfma_f32_16x16x32_bf16 v[26:29], v[152:155], v[208:211], v[26:29]
	v_mfma_f32_16x16x32_bf16 v[14:17], v[140:143], v[216:219], v[14:17]
	v_mfma_f32_16x16x32_bf16 v[10:13], v[152:155], v[216:219], v[10:13]
	v_mfma_f32_16x16x32_bf16 v[62:65], v[148:151], v[180:183], v[62:65]
	v_mfma_f32_16x16x32_bf16 v[58:61], v[156:159], v[180:183], v[58:61]
	v_mfma_f32_16x16x32_bf16 v[46:49], v[148:151], v[204:207], v[46:49]
	v_mfma_f32_16x16x32_bf16 v[42:45], v[156:159], v[204:207], v[42:45]
	v_mfma_f32_16x16x32_bf16 v[30:33], v[148:151], v[212:215], v[30:33]
	v_mfma_f32_16x16x32_bf16 v[26:29], v[156:159], v[212:215], v[26:29]
	v_mfma_f32_16x16x32_bf16 v[14:17], v[148:151], v[220:223], v[14:17]
	v_mfma_f32_16x16x32_bf16 v[10:13], v[156:159], v[220:223], v[10:13]
	s_setprio 0
	s_setprio 1
	v_mfma_f32_16x16x32_bf16 v[54:57], v[160:163], v[176:179], v[54:57]
	v_mfma_f32_16x16x32_bf16 v[50:53], v[168:171], v[176:179], v[50:53]
	v_mfma_f32_16x16x32_bf16 v[38:41], v[160:163], v[200:203], v[38:41]
	v_mfma_f32_16x16x32_bf16 v[34:37], v[168:171], v[200:203], v[34:37]
	v_mfma_f32_16x16x32_bf16 v[22:25], v[160:163], v[208:211], v[22:25]
	v_mfma_f32_16x16x32_bf16 v[18:21], v[168:171], v[208:211], v[18:21]
	v_mfma_f32_16x16x32_bf16 v[6:9], v[160:163], v[216:219], v[6:9]
	v_mfma_f32_16x16x32_bf16 v[2:5], v[168:171], v[216:219], v[2:5]
	v_mfma_f32_16x16x32_bf16 v[54:57], v[164:167], v[180:183], v[54:57]
	v_mfma_f32_16x16x32_bf16 v[50:53], v[172:175], v[180:183], v[50:53]
	v_mfma_f32_16x16x32_bf16 v[38:41], v[164:167], v[204:207], v[38:41]
	v_mfma_f32_16x16x32_bf16 v[34:37], v[172:175], v[204:207], v[34:37]
	v_mfma_f32_16x16x32_bf16 v[22:25], v[164:167], v[212:215], v[22:25]
	v_mfma_f32_16x16x32_bf16 v[18:21], v[172:175], v[212:215], v[18:21]
	v_mfma_f32_16x16x32_bf16 v[6:9], v[164:167], v[220:223], v[6:9]
	v_mfma_f32_16x16x32_bf16 v[2:5], v[172:175], v[220:223], v[2:5]
	s_setprio 0
	s_barrier
	s_add_i32 s74, 0, 0x18000
	s_add_i32 s75, 0, 0x1c000
	v_add_u32_e32 v156, s74, v145
	v_add_u32_e32 v172, s75, v145
	ds_read_b128 v[140:143], v156
	ds_read_b128 v[148:151], v156 offset:1024
	ds_read_b128 v[152:155], v156 offset:2048
	ds_read_b128 v[156:159], v156 offset:3072
	ds_read_b128 v[160:163], v172
	ds_read_b128 v[164:167], v172 offset:1024
	ds_read_b128 v[168:171], v172 offset:2048
	ds_read_b128 v[172:175], v172 offset:3072
	s_add_u32 s60, s60, 0x80000
	s_addc_u32 s61, s61, 0
	s_mov_b32 m0, s64
	ds_read_b128 v[176:179], v147 offset:32768
	ds_read_b128 v[180:183], v147 offset:33792
	ds_read_b128 v[200:203], v147 offset:34816
	ds_read_b128 v[204:207], v147 offset:35840
	ds_read_b128 v[208:211], v147 offset:36864
	ds_read_b128 v[212:215], v147 offset:37888
	ds_read_b128 v[216:219], v147 offset:38912
	ds_read_b128 v[220:223], v147 offset:39936
	global_load_lds_dwordx4 v130, s[60:61]
	s_mov_b32 m0, s65
	s_nop 0
	global_load_lds_dwordx4 v132, s[60:61]
	s_waitcnt vmcnt(8)
	s_waitcnt lgkmcnt(0)
	s_barrier
	s_setprio 1
	s_waitcnt lgkmcnt(0)
	v_mfma_f32_16x16x32_bf16 v[126:129], v[140:143], v[176:179], v[126:129]
	v_mfma_f32_16x16x32_bf16 v[122:125], v[152:155], v[176:179], v[122:125]
	v_mfma_f32_16x16x32_bf16 v[110:113], v[140:143], v[200:203], v[110:113]
	v_mfma_f32_16x16x32_bf16 v[106:109], v[152:155], v[200:203], v[106:109]
	v_mfma_f32_16x16x32_bf16 v[94:97], v[140:143], v[208:211], v[94:97]
	v_mfma_f32_16x16x32_bf16 v[90:93], v[152:155], v[208:211], v[90:93]
	v_mfma_f32_16x16x32_bf16 v[78:81], v[140:143], v[216:219], v[78:81]
	v_mfma_f32_16x16x32_bf16 v[74:77], v[152:155], v[216:219], v[74:77]
	v_mfma_f32_16x16x32_bf16 v[126:129], v[148:151], v[180:183], v[126:129]
	v_mfma_f32_16x16x32_bf16 v[122:125], v[156:159], v[180:183], v[122:125]
	v_mfma_f32_16x16x32_bf16 v[110:113], v[148:151], v[204:207], v[110:113]
	v_mfma_f32_16x16x32_bf16 v[106:109], v[156:159], v[204:207], v[106:109]
	v_mfma_f32_16x16x32_bf16 v[94:97], v[148:151], v[212:215], v[94:97]
	v_mfma_f32_16x16x32_bf16 v[90:93], v[156:159], v[212:215], v[90:93]
	v_mfma_f32_16x16x32_bf16 v[78:81], v[148:151], v[220:223], v[78:81]
	v_mfma_f32_16x16x32_bf16 v[74:77], v[156:159], v[220:223], v[74:77]
	s_setprio 0
	s_setprio 1
	v_mfma_f32_16x16x32_bf16 v[118:121], v[160:163], v[176:179], v[118:121]
	v_mfma_f32_16x16x32_bf16 v[114:117], v[168:171], v[176:179], v[114:117]
	v_mfma_f32_16x16x32_bf16 v[102:105], v[160:163], v[200:203], v[102:105]
	v_mfma_f32_16x16x32_bf16 v[98:101], v[168:171], v[200:203], v[98:101]
	v_mfma_f32_16x16x32_bf16 v[86:89], v[160:163], v[208:211], v[86:89]
	v_mfma_f32_16x16x32_bf16 v[82:85], v[168:171], v[208:211], v[82:85]
	v_mfma_f32_16x16x32_bf16 v[70:73], v[160:163], v[216:219], v[70:73]
	v_mfma_f32_16x16x32_bf16 v[66:69], v[168:171], v[216:219], v[66:69]
	v_mfma_f32_16x16x32_bf16 v[118:121], v[164:167], v[180:183], v[118:121]
	v_mfma_f32_16x16x32_bf16 v[114:117], v[172:175], v[180:183], v[114:117]
	v_mfma_f32_16x16x32_bf16 v[102:105], v[164:167], v[204:207], v[102:105]
	v_mfma_f32_16x16x32_bf16 v[98:101], v[172:175], v[204:207], v[98:101]
	v_mfma_f32_16x16x32_bf16 v[86:89], v[164:167], v[212:215], v[86:89]
	v_mfma_f32_16x16x32_bf16 v[82:85], v[172:175], v[212:215], v[82:85]
	v_mfma_f32_16x16x32_bf16 v[70:73], v[164:167], v[220:223], v[70:73]
	v_mfma_f32_16x16x32_bf16 v[66:69], v[172:175], v[220:223], v[66:69]
	s_setprio 0
	s_barrier
; #define PG8_STAGE(bufoff, gbase, voff) do { _Pragma("unroll") for (int _i = 0; _i < 2; ++_i) \
;         __builtin_amdgcn_global_load_lds((const unsigned*)((const char*)(gbase) + (voff)[_i]), (LAS unsigned*)(lds + (bufoff) + ldsw + _i * 8192), 16, 0, 0); } while (0)
; #define PG8_LDA(dst, b, h) do { _Pragma("unroll") for (int m = 0; m < 4; ++m) _Pragma("unroll") for (int k = 0; k < 2; ++k) dst[m][k] = *(const LAS bf16x8*)(lds + PG8_SA(b, h) + aoff + m * 2048 + k * 1024); } while (0)
; #define PG8_MMA(ai, bj, At, Bt) do { __builtin_amdgcn_s_setprio(1); _Pragma("unroll") for (int m = 0; m < 4; ++m) _Pragma("unroll") for (int n = 0; n < 2; ++n) _Pragma("unroll") for (int k = 0; k < 2; ++k) \
;         acc[ai][bj][m][n] = __builtin_amdgcn_mfma_f32_16x16x32_bf16(Bt[n][k], At[m][k], acc[ai][bj][m][n], 0, 0, 0); __builtin_amdgcn_s_setprio(0); } while (0)
; #define PG8_WAIT_V(n) asm volatile("s_waitcnt vmcnt(" #n ")" ::: "memory")
; #define PG8_WAIT_L(n) asm volatile("s_waitcnt lgkmcnt(" #n ")" ::: "memory")
; #define PG8_BAR __builtin_amdgcn_s_barrier()
; #define PG8_SCHED __builtin_amdgcn_sched_barrier(0)
; template <class Epi, class Sched, bool ALIGN_EPI = false, bool SP2 = false>
; __device__ __forceinline__ void gemm_phase(LAS unsigned char* lds, const Gemm g, const Sched& S, const Epi& E, const int tid_) {
;     ...
;             PG8_LDA(At, 1, 1); PG8_STAGE(PG8_SB(1, 0), b3, voffB); PG8_STAGE(PG8_SB(1, 1), b3 + hstep, voffB); PG8_STAGE(PG8_SA(1, 0), a3, voffA);
;             PG8_WAIT_V(8); PG8_WAIT_L(0); PG8_BAR; PG8_MMA(1, 0, At, B0); PG8_MMA(1, 1, At, B1); PG8_BAR; PG8_SCHED;
	s_add_i32 s60, s74, s62
	s_add_i32 m0, s60, 0xffffff80
	ds_read_b128 v[176:179], v147 offset:49152
	ds_read_b128 v[180:183], v147 offset:50176
	ds_read_b128 v[200:203], v147 offset:51200
	ds_read_b128 v[204:207], v147 offset:52224
	ds_read_b128 v[208:211], v147 offset:53248
	ds_read_b128 v[212:215], v147 offset:54272
	ds_read_b128 v[216:219], v147 offset:55296
	ds_read_b128 v[220:223], v147 offset:56320
	global_load_lds_dwordx4 v0, s[58:59] offset:128
	s_add_i32 m0, s60, 0x2000
	s_add_u32 s58, s58, 0x80080
	v_lshl_add_u64 v[184:185], v[224:225], 0, s[96:97]
	s_addc_u32 s59, s59, 0
	s_add_i32 s60, s75, s62
	global_load_lds_dwordx4 v[184:185], off
	s_mov_b32 m0, s60
	s_nop 0
	global_load_lds_dwordx4 v0, s[58:59]
	s_add_i32 m0, s60, 0x2000
	s_nop 0
	global_load_lds_dwordx4 v134, s[58:59]
	v_lshl_add_u64 v[184:185], v[236:237], 0, s[96:97]
	s_mov_b32 m0, s67
	s_nop 0
	global_load_lds_dwordx4 v[184:185], off
	v_lshl_add_u64 v[184:185], v[242:243], 0, s[96:97]
	s_mov_b32 m0, s68
	s_nop 0
	global_load_lds_dwordx4 v[184:185], off
	s_waitcnt vmcnt(8)
	s_waitcnt lgkmcnt(0)
	s_barrier
	s_setprio 1
	s_waitcnt lgkmcnt(0)
	v_mfma_f32_16x16x32_bf16 v[62:65], v[140:143], v[176:179], v[62:65]
	v_mfma_f32_16x16x32_bf16 v[58:61], v[152:155], v[176:179], v[58:61]
	v_mfma_f32_16x16x32_bf16 v[46:49], v[140:143], v[200:203], v[46:49]
	v_mfma_f32_16x16x32_bf16 v[42:45], v[152:155], v[200:203], v[42:45]
	v_mfma_f32_16x16x32_bf16 v[30:33], v[140:143], v[208:211], v[30:33]
	v_mfma_f32_16x16x32_bf16 v[26:29], v[152:155], v[208:211], v[26:29]
	v_mfma_f32_16x16x32_bf16 v[14:17], v[140:143], v[216:219], v[14:17]
	v_mfma_f32_16x16x32_bf16 v[10:13], v[152:155], v[216:219], v[10:13]
	v_mfma_f32_16x16x32_bf16 v[62:65], v[148:151], v[180:183], v[62:65]
	v_mfma_f32_16x16x32_bf16 v[58:61], v[156:159], v[180:183], v[58:61]
	v_mfma_f32_16x16x32_bf16 v[46:49], v[148:151], v[204:207], v[46:49]
	v_mfma_f32_16x16x32_bf16 v[42:45], v[156:159], v[204:207], v[42:45]
	v_mfma_f32_16x16x32_bf16 v[30:33], v[148:151], v[212:215], v[30:33]
	v_mfma_f32_16x16x32_bf16 v[26:29], v[156:159], v[212:215], v[26:29]
	v_mfma_f32_16x16x32_bf16 v[14:17], v[148:151], v[220:223], v[14:17]
	v_mfma_f32_16x16x32_bf16 v[10:13], v[156:159], v[220:223], v[10:13]
	s_setprio 0
	s_setprio 1
	v_mfma_f32_16x16x32_bf16 v[54:57], v[160:163], v[176:179], v[54:57]
	v_mfma_f32_16x16x32_bf16 v[50:53], v[168:171], v[176:179], v[50:53]
	v_mfma_f32_16x16x32_bf16 v[38:41], v[160:163], v[200:203], v[38:41]
	v_mfma_f32_16x16x32_bf16 v[34:37], v[168:171], v[200:203], v[34:37]
	v_mfma_f32_16x16x32_bf16 v[22:25], v[160:163], v[208:211], v[22:25]
	v_mfma_f32_16x16x32_bf16 v[18:21], v[168:171], v[208:211], v[18:21]
	v_mfma_f32_16x16x32_bf16 v[6:9], v[160:163], v[216:219], v[6:9]
	v_mfma_f32_16x16x32_bf16 v[2:5], v[168:171], v[216:219], v[2:5]
	v_mfma_f32_16x16x32_bf16 v[54:57], v[164:167], v[180:183], v[54:57]
	v_mfma_f32_16x16x32_bf16 v[50:53], v[172:175], v[180:183], v[50:53]
	v_mfma_f32_16x16x32_bf16 v[38:41], v[164:167], v[204:207], v[38:41]
	v_mfma_f32_16x16x32_bf16 v[34:37], v[172:175], v[204:207], v[34:37]
	v_mfma_f32_16x16x32_bf16 v[22:25], v[164:167], v[212:215], v[22:25]
	v_mfma_f32_16x16x32_bf16 v[18:21], v[172:175], v[212:215], v[18:21]
	v_mfma_f32_16x16x32_bf16 v[6:9], v[164:167], v[220:223], v[6:9]
	v_mfma_f32_16x16x32_bf16 v[2:5], v[172:175], v[220:223], v[2:5]
	s_setprio 0
	s_barrier
	s_add_i32 s73, s73, 2
	s_add_u32 s54, s54, 0x100
	s_addc_u32 s55, s55, 0
	s_add_u32 s49, s49, 0x100
	s_addc_u32 s72, s72, 0
	s_cmp_gt_u32 s73, 29
	s_cbranch_scc0 .LBB0_253
	s_and_b64 vcc, exec, s[10:11]
	s_cbranch_vccz .LBB0_256
	s_barrier

; #define PG8_STAGE(bufoff, gbase, voff) do { _Pragma("unroll") for (int _i = 0; _i < 2; ++_i) \
;         __builtin_amdgcn_global_load_lds((const unsigned*)((const char*)(gbase) + (voff)[_i]), (LAS unsigned*)(lds + (bufoff) + ldsw + _i * 8192), 16, 0, 0); } while (0)
; #define PG8_LDA(dst, b, h) do { _Pragma("unroll") for (int m = 0; m < 4; ++m) _Pragma("unroll") for (int k = 0; k < 2; ++k) dst[m][k] = *(const LAS bf16x8*)(lds + PG8_SA(b, h) + aoff + m * 2048 + k * 1024); } while (0)
; #define PG8_LDB(dst, b, h) do { _Pragma("unroll") for (int n = 0; n < 2; ++n) _Pragma("unroll") for (int k = 0; k < 2; ++k) dst[n][k] = *(const LAS bf16x8*)(lds + PG8_SB(b, h) + boff + n * 2048 + k * 1024); } while (0)
; #define PG8_MMA(ai, bj, At, Bt) do { __builtin_amdgcn_s_setprio(1); _Pragma("unroll") for (int m = 0; m < 4; ++m) _Pragma("unroll") for (int n = 0; n < 2; ++n) _Pragma("unroll") for (int k = 0; k < 2; ++k) \
;         acc[ai][bj][m][n] = __builtin_amdgcn_mfma_f32_16x16x32_bf16(Bt[n][k], At[m][k], acc[ai][bj][m][n], 0, 0, 0); __builtin_amdgcn_s_setprio(0); } while (0)
; #define PG8_WAIT_V(n) asm volatile("s_waitcnt vmcnt(" #n ")" ::: "memory")
; #define PG8_WAIT_L(n) asm volatile("s_waitcnt lgkmcnt(" #n ")" ::: "memory")
; #define PG8_BAR __builtin_amdgcn_s_barrier()
; #define PG8_SCHED __builtin_amdgcn_sched_barrier(0)
; template <class Epi, class Sched, bool ALIGN_EPI = false, bool SP2 = false>
; __device__ __forceinline__ void gemm_phase(LAS unsigned char* lds, const Gemm g, const Sched& S, const Epi& E, const int tid_) {
;     ...
;             if constexpr (SP2) {
;             PG8_LDB(B0, 0, 0); PG8_LDB(B1, 0, 1); PG8_SCHED; PG8_LDA(At, 0, 0); PG8_STAGE(PG8_SA(1, 1), a1 + hstep, voffA);
;             PG8_WAIT_V(8); PG8_WAIT_L(0); PG8_BAR; PG8_MMA(0, 0, At, B0); PG8_MMA(0, 1, At, B1); PG8_BAR; PG8_SCHED;
;             PG8_LDA(At, 0, 1); PG8_STAGE(PG8_SB(0, 0), b2, voffB); PG8_STAGE(PG8_SB(0, 1), b2 + hstep, voffB); PG8_STAGE(PG8_SA(0, 0), a2, voffA);
;             PG8_WAIT_V(8); PG8_WAIT_L(0); PG8_BAR; PG8_MMA(1, 0, At, B0); PG8_MMA(1, 1, At, B1); PG8_BAR; PG8_SCHED;
.LBB0_359:
	s_add_u32 s48, s46, 0x100
	s_addc_u32 s49, s47, 0
	s_add_i32 s68, 0, 0x10000
	s_cmpk_eq_i32 s67, 0x7c
	s_cselect_b32 s53, s17, s49
	s_cselect_b32 s52, s21, s48
	s_cselect_b32 s51, s15, s66
	s_cselect_b32 s50, s64, s65
	s_add_i32 s69, 0, 0x14000
	v_add_u32_e32 v148, s68, v157
	v_add_u32_e32 v168, s69, v157
	ds_read_b128 v[130:133], v148
	ds_read_b128 v[134:137], v148 offset:1024
	ds_read_b128 v[138:141], v148 offset:2048
	ds_read_b128 v[148:151], v148 offset:3072
	ds_read_b128 v[152:155], v168
	ds_read_b128 v[160:163], v168 offset:1024
	ds_read_b128 v[164:167], v168 offset:2048
	ds_read_b128 v[168:171], v168 offset:3072
	s_add_i32 m0, s45, 0xc000
	ds_read_b128 v[172:175], v159
	ds_read_b128 v[176:179], v159 offset:1024
	ds_read_b128 v[180:183], v159 offset:2048
	ds_read_b128 v[200:203], v159 offset:3072
	ds_read_b128 v[204:207], v159 offset:4096
	ds_read_b128 v[208:211], v159 offset:5120
	ds_read_b128 v[212:215], v159 offset:6144
	ds_read_b128 v[216:219], v159 offset:7168
	global_load_lds_dwordx4 v144, s[46:47]
	s_add_i32 m0, s45, 0xe000
	s_nop 0
	global_load_lds_dwordx4 v146, s[46:47]
	s_waitcnt vmcnt(8)
	s_waitcnt lgkmcnt(0)
	s_barrier
	s_setprio 1
	s_waitcnt lgkmcnt(0)
	v_mfma_f32_16x16x32_bf16 v[126:129], v[130:133], v[172:175], v[126:129]
	v_mfma_f32_16x16x32_bf16 v[122:125], v[138:141], v[172:175], v[122:125]
	v_mfma_f32_16x16x32_bf16 v[118:121], v[130:133], v[180:183], v[118:121]
	v_mfma_f32_16x16x32_bf16 v[106:109], v[138:141], v[180:183], v[106:109]
	v_mfma_f32_16x16x32_bf16 v[102:105], v[130:133], v[204:207], v[102:105]
	v_mfma_f32_16x16x32_bf16 v[90:93], v[138:141], v[204:207], v[90:93]
	v_mfma_f32_16x16x32_bf16 v[86:89], v[130:133], v[212:215], v[86:89]
	v_mfma_f32_16x16x32_bf16 v[74:77], v[138:141], v[212:215], v[74:77]
	v_mfma_f32_16x16x32_bf16 v[126:129], v[134:137], v[176:179], v[126:129]
	v_mfma_f32_16x16x32_bf16 v[122:125], v[148:151], v[176:179], v[122:125]
	v_mfma_f32_16x16x32_bf16 v[118:121], v[134:137], v[200:203], v[118:121]
	v_mfma_f32_16x16x32_bf16 v[106:109], v[148:151], v[200:203], v[106:109]
	v_mfma_f32_16x16x32_bf16 v[102:105], v[134:137], v[208:211], v[102:105]
	v_mfma_f32_16x16x32_bf16 v[90:93], v[148:151], v[208:211], v[90:93]
	v_mfma_f32_16x16x32_bf16 v[86:89], v[134:137], v[216:219], v[86:89]
	v_mfma_f32_16x16x32_bf16 v[74:77], v[148:151], v[216:219], v[74:77]
	s_setprio 0
	s_setprio 1
	v_mfma_f32_16x16x32_bf16 v[114:117], v[152:155], v[172:175], v[114:117]
	v_mfma_f32_16x16x32_bf16 v[110:113], v[164:167], v[172:175], v[110:113]
	v_mfma_f32_16x16x32_bf16 v[98:101], v[152:155], v[180:183], v[98:101]
	v_mfma_f32_16x16x32_bf16 v[94:97], v[164:167], v[180:183], v[94:97]
	v_mfma_f32_16x16x32_bf16 v[82:85], v[152:155], v[204:207], v[82:85]
	v_mfma_f32_16x16x32_bf16 v[78:81], v[164:167], v[204:207], v[78:81]
	v_mfma_f32_16x16x32_bf16 v[70:73], v[152:155], v[212:215], v[70:73]
	v_mfma_f32_16x16x32_bf16 v[66:69], v[164:167], v[212:215], v[66:69]
	v_mfma_f32_16x16x32_bf16 v[114:117], v[160:163], v[176:179], v[114:117]
	v_mfma_f32_16x16x32_bf16 v[110:113], v[168:171], v[176:179], v[110:113]
	v_mfma_f32_16x16x32_bf16 v[98:101], v[160:163], v[200:203], v[98:101]
	v_mfma_f32_16x16x32_bf16 v[94:97], v[168:171], v[200:203], v[94:97]
	v_mfma_f32_16x16x32_bf16 v[82:85], v[160:163], v[208:211], v[82:85]
	v_mfma_f32_16x16x32_bf16 v[78:81], v[168:171], v[208:211], v[78:81]
	v_mfma_f32_16x16x32_bf16 v[70:73], v[160:163], v[216:219], v[70:73]
	v_mfma_f32_16x16x32_bf16 v[66:69], v[168:171], v[216:219], v[66:69]
	s_setprio 0
	s_barrier
	s_add_i32 s46, s68, s55
	s_mov_b32 m0, s46
	ds_read_b128 v[172:175], v159 offset:16384
	ds_read_b128 v[176:179], v159 offset:17408
	ds_read_b128 v[180:183], v159 offset:18432
	ds_read_b128 v[200:203], v159 offset:19456
	ds_read_b128 v[204:207], v159 offset:20480
	ds_read_b128 v[208:211], v159 offset:21504
	ds_read_b128 v[212:215], v159 offset:22528
	ds_read_b128 v[216:219], v159 offset:23552
	global_load_lds_dwordx4 v0, s[50:51]
	s_add_i32 m0, s46, 0x2000
	s_add_u32 s46, s50, 0x200000
	v_lshl_add_u64 v[192:193], s[50:51], 0, v[142:143]
	s_addc_u32 s47, s51, 0
	s_add_i32 s68, s69, s55
	global_load_lds_dwordx4 v142, s[50:51]
	s_mov_b32 m0, s68
	s_nop 0
	global_load_lds_dwordx4 v0, s[46:47]
	s_add_i32 m0, s68, 0x2000
	s_nop 0
	global_load_lds_dwordx4 v142, s[46:47]
	s_mov_b32 m0, s45
	s_nop 0
	global_load_lds_dwordx4 v0, s[52:53]
	s_mov_b32 m0, s56
	s_nop 0
	global_load_lds_dwordx4 v142, s[52:53]
	s_waitcnt vmcnt(8)
	s_waitcnt lgkmcnt(0)
	s_barrier
	s_setprio 1
	s_waitcnt lgkmcnt(0)
	v_mfma_f32_16x16x32_bf16 v[62:65], v[130:133], v[172:175], v[62:65]
	v_mfma_f32_16x16x32_bf16 v[58:61], v[138:141], v[172:175], v[58:61]
	v_mfma_f32_16x16x32_bf16 v[54:57], v[130:133], v[180:183], v[54:57]
	v_mfma_f32_16x16x32_bf16 v[42:45], v[138:141], v[180:183], v[42:45]
	v_mfma_f32_16x16x32_bf16 v[38:41], v[130:133], v[204:207], v[38:41]
	v_mfma_f32_16x16x32_bf16 v[26:29], v[138:141], v[204:207], v[26:29]
	v_mfma_f32_16x16x32_bf16 v[22:25], v[130:133], v[212:215], v[22:25]
	v_mfma_f32_16x16x32_bf16 v[10:13], v[138:141], v[212:215], v[10:13]
	v_mfma_f32_16x16x32_bf16 v[62:65], v[134:137], v[176:179], v[62:65]
	v_mfma_f32_16x16x32_bf16 v[58:61], v[148:151], v[176:179], v[58:61]
	v_mfma_f32_16x16x32_bf16 v[54:57], v[134:137], v[200:203], v[54:57]
	v_mfma_f32_16x16x32_bf16 v[42:45], v[148:151], v[200:203], v[42:45]
	v_mfma_f32_16x16x32_bf16 v[38:41], v[134:137], v[208:211], v[38:41]
	v_mfma_f32_16x16x32_bf16 v[26:29], v[148:151], v[208:211], v[26:29]
	v_mfma_f32_16x16x32_bf16 v[22:25], v[134:137], v[216:219], v[22:25]
	v_mfma_f32_16x16x32_bf16 v[10:13], v[148:151], v[216:219], v[10:13]
	s_setprio 0
	s_setprio 1
	v_mfma_f32_16x16x32_bf16 v[50:53], v[152:155], v[172:175], v[50:53]
	v_mfma_f32_16x16x32_bf16 v[46:49], v[164:167], v[172:175], v[46:49]
	v_mfma_f32_16x16x32_bf16 v[34:37], v[152:155], v[180:183], v[34:37]
	v_mfma_f32_16x16x32_bf16 v[30:33], v[164:167], v[180:183], v[30:33]
	v_mfma_f32_16x16x32_bf16 v[18:21], v[152:155], v[204:207], v[18:21]
	v_mfma_f32_16x16x32_bf16 v[14:17], v[164:167], v[204:207], v[14:17]
	v_mfma_f32_16x16x32_bf16 v[6:9], v[152:155], v[212:215], v[6:9]
	v_mfma_f32_16x16x32_bf16 v[2:5], v[164:167], v[212:215], v[2:5]
	v_mfma_f32_16x16x32_bf16 v[50:53], v[160:163], v[176:179], v[50:53]
	v_mfma_f32_16x16x32_bf16 v[46:49], v[168:171], v[176:179], v[46:49]
	v_mfma_f32_16x16x32_bf16 v[34:37], v[160:163], v[200:203], v[34:37]
	v_mfma_f32_16x16x32_bf16 v[30:33], v[168:171], v[200:203], v[30:33]
	v_mfma_f32_16x16x32_bf16 v[18:21], v[160:163], v[208:211], v[18:21]
	v_mfma_f32_16x16x32_bf16 v[14:17], v[168:171], v[208:211], v[14:17]
	v_mfma_f32_16x16x32_bf16 v[6:9], v[160:163], v[216:219], v[6:9]
	v_mfma_f32_16x16x32_bf16 v[2:5], v[168:171], v[216:219], v[2:5]
	s_setprio 0
	s_barrier
; #define PG8_STAGE(bufoff, gbase, voff) do { _Pragma("unroll") for (int _i = 0; _i < 2; ++_i) \
;         __builtin_amdgcn_global_load_lds((const unsigned*)((const char*)(gbase) + (voff)[_i]), (LAS unsigned*)(lds + (bufoff) + ldsw + _i * 8192), 16, 0, 0); } while (0)
; #define PG8_LDA(dst, b, h) do { _Pragma("unroll") for (int m = 0; m < 4; ++m) _Pragma("unroll") for (int k = 0; k < 2; ++k) dst[m][k] = *(const LAS bf16x8*)(lds + PG8_SA(b, h) + aoff + m * 2048 + k * 1024); } while (0)
; #define PG8_LDB(dst, b, h) do { _Pragma("unroll") for (int n = 0; n < 2; ++n) _Pragma("unroll") for (int k = 0; k < 2; ++k) dst[n][k] = *(const LAS bf16x8*)(lds + PG8_SB(b, h) + boff + n * 2048 + k * 1024); } while (0)
; #define PG8_MMA(ai, bj, At, Bt) do { __builtin_amdgcn_s_setprio(1); _Pragma("unroll") for (int m = 0; m < 4; ++m) _Pragma("unroll") for (int n = 0; n < 2; ++n) _Pragma("unroll") for (int k = 0; k < 2; ++k) \
;         acc[ai][bj][m][n] = __builtin_amdgcn_mfma_f32_16x16x32_bf16(Bt[n][k], At[m][k], acc[ai][bj][m][n], 0, 0, 0); __builtin_amdgcn_s_setprio(0); } while (0)
; #define PG8_WAIT_V(n) asm volatile("s_waitcnt vmcnt(" #n ")" ::: "memory")
; #define PG8_WAIT_L(n) asm volatile("s_waitcnt lgkmcnt(" #n ")" ::: "memory")
; #define PG8_BAR __builtin_amdgcn_s_barrier()
; #define PG8_SCHED __builtin_amdgcn_sched_barrier(0)
; template <class Epi, class Sched, bool ALIGN_EPI = false, bool SP2 = false>
; __device__ __forceinline__ void gemm_phase(LAS unsigned char* lds, const Gemm g, const Sched& S, const Epi& E, const int tid_) {
;     ...
;             PG8_LDB(B0, 1, 0); PG8_LDB(B1, 1, 1); PG8_SCHED; PG8_LDA(At, 1, 0); PG8_STAGE(PG8_SA(0, 1), a2 + hstep, voffA);
;             PG8_WAIT_V(8); PG8_WAIT_L(0); PG8_BAR; PG8_MMA(0, 0, At, B0); PG8_MMA(0, 1, At, B1); PG8_BAR; PG8_SCHED;
;             PG8_LDA(At, 1, 1); PG8_STAGE(PG8_SB(1, 0), b3, voffB); PG8_STAGE(PG8_SB(1, 1), b3 + hstep, voffB); PG8_STAGE(PG8_SA(1, 0), a3, voffA);
;             PG8_WAIT_V(8); PG8_WAIT_L(0); PG8_BAR; PG8_MMA(1, 0, At, B0); PG8_MMA(1, 1, At, B1); PG8_BAR; PG8_SCHED;
	s_add_i32 s68, 0, 0x18000
	s_add_i32 s69, 0, 0x1c000
	v_add_u32_e32 v148, s68, v157
	v_add_u32_e32 v168, s69, v157
	ds_read_b128 v[130:133], v148
	ds_read_b128 v[134:137], v148 offset:1024
	ds_read_b128 v[138:141], v148 offset:2048
	ds_read_b128 v[148:151], v148 offset:3072
	ds_read_b128 v[152:155], v168
	ds_read_b128 v[160:163], v168 offset:1024
	ds_read_b128 v[164:167], v168 offset:2048
	ds_read_b128 v[168:171], v168 offset:3072
	s_add_u32 s46, s52, 0x200000
	s_addc_u32 s47, s53, 0
	s_mov_b32 m0, s57
	ds_read_b128 v[172:175], v159 offset:32768
	ds_read_b128 v[176:179], v159 offset:33792
	ds_read_b128 v[180:183], v159 offset:34816
	ds_read_b128 v[200:203], v159 offset:35840
	ds_read_b128 v[204:207], v159 offset:36864
	ds_read_b128 v[208:211], v159 offset:37888
	ds_read_b128 v[212:215], v159 offset:38912
	ds_read_b128 v[216:219], v159 offset:39936
	global_load_lds_dwordx4 v0, s[46:47]
	s_mov_b32 m0, s58
	s_nop 0
	global_load_lds_dwordx4 v142, s[46:47]
	s_waitcnt vmcnt(8)
	s_waitcnt lgkmcnt(0)
	s_barrier
	s_setprio 1
	s_waitcnt lgkmcnt(0)
	v_mfma_f32_16x16x32_bf16 v[126:129], v[130:133], v[172:175], v[126:129]
	v_mfma_f32_16x16x32_bf16 v[122:125], v[138:141], v[172:175], v[122:125]
	v_mfma_f32_16x16x32_bf16 v[118:121], v[130:133], v[180:183], v[118:121]
	v_mfma_f32_16x16x32_bf16 v[106:109], v[138:141], v[180:183], v[106:109]
	v_mfma_f32_16x16x32_bf16 v[102:105], v[130:133], v[204:207], v[102:105]
	v_mfma_f32_16x16x32_bf16 v[90:93], v[138:141], v[204:207], v[90:93]
	v_mfma_f32_16x16x32_bf16 v[86:89], v[130:133], v[212:215], v[86:89]
	v_mfma_f32_16x16x32_bf16 v[74:77], v[138:141], v[212:215], v[74:77]
	v_mfma_f32_16x16x32_bf16 v[126:129], v[134:137], v[176:179], v[126:129]
	v_mfma_f32_16x16x32_bf16 v[122:125], v[148:151], v[176:179], v[122:125]
	v_mfma_f32_16x16x32_bf16 v[118:121], v[134:137], v[200:203], v[118:121]
	v_mfma_f32_16x16x32_bf16 v[106:109], v[148:151], v[200:203], v[106:109]
	v_mfma_f32_16x16x32_bf16 v[102:105], v[134:137], v[208:211], v[102:105]
	v_mfma_f32_16x16x32_bf16 v[90:93], v[148:151], v[208:211], v[90:93]
	v_mfma_f32_16x16x32_bf16 v[86:89], v[134:137], v[216:219], v[86:89]
	v_mfma_f32_16x16x32_bf16 v[74:77], v[148:151], v[216:219], v[74:77]
	s_setprio 0
	s_setprio 1
	v_mfma_f32_16x16x32_bf16 v[114:117], v[152:155], v[172:175], v[114:117]
	v_mfma_f32_16x16x32_bf16 v[110:113], v[164:167], v[172:175], v[110:113]
	v_mfma_f32_16x16x32_bf16 v[98:101], v[152:155], v[180:183], v[98:101]
	v_mfma_f32_16x16x32_bf16 v[94:97], v[164:167], v[180:183], v[94:97]
	v_mfma_f32_16x16x32_bf16 v[82:85], v[152:155], v[204:207], v[82:85]
	v_mfma_f32_16x16x32_bf16 v[78:81], v[164:167], v[204:207], v[78:81]
	v_mfma_f32_16x16x32_bf16 v[70:73], v[152:155], v[212:215], v[70:73]
	v_mfma_f32_16x16x32_bf16 v[66:69], v[164:167], v[212:215], v[66:69]
	v_mfma_f32_16x16x32_bf16 v[114:117], v[160:163], v[176:179], v[114:117]
	v_mfma_f32_16x16x32_bf16 v[110:113], v[168:171], v[176:179], v[110:113]
	v_mfma_f32_16x16x32_bf16 v[98:101], v[160:163], v[200:203], v[98:101]
	v_mfma_f32_16x16x32_bf16 v[94:97], v[168:171], v[200:203], v[94:97]
	v_mfma_f32_16x16x32_bf16 v[82:85], v[160:163], v[208:211], v[82:85]
	v_mfma_f32_16x16x32_bf16 v[78:81], v[168:171], v[208:211], v[78:81]
	v_mfma_f32_16x16x32_bf16 v[70:73], v[160:163], v[216:219], v[70:73]
	v_mfma_f32_16x16x32_bf16 v[66:69], v[168:171], v[216:219], v[66:69]
	s_setprio 0
	s_barrier
	s_add_i32 s46, s68, s55
	s_add_i32 m0, s46, 0xffffff80
	ds_read_b128 v[172:175], v159 offset:49152
	ds_read_b128 v[176:179], v159 offset:50176
	ds_read_b128 v[180:183], v159 offset:51200
	ds_read_b128 v[200:203], v159 offset:52224
	ds_read_b128 v[204:207], v159 offset:53248
	ds_read_b128 v[208:211], v159 offset:54272
	ds_read_b128 v[212:215], v159 offset:55296
	ds_read_b128 v[216:219], v159 offset:56320
	global_load_lds_dwordx4 v0, s[50:51] offset:128
	s_add_i32 m0, s46, 0x2000
	s_add_u32 s46, s50, 0x200080
	v_lshl_add_u64 v[184:185], v[192:193], 0, s[96:97]
	s_addc_u32 s47, s51, 0
	s_add_i32 s50, s69, s55
	global_load_lds_dwordx4 v[184:185], off
	s_mov_b32 m0, s50
	s_nop 0
	global_load_lds_dwordx4 v0, s[46:47]
	s_add_i32 m0, s50, 0x2000
	s_nop 0
	global_load_lds_dwordx4 v142, s[46:47]
	s_add_i32 m0, s60, 0xffffff80
	s_nop 0
	global_load_lds_dwordx4 v0, s[52:53] offset:128
	s_add_i32 m0, s61, 0xffffff80
	s_nop 0
	global_load_lds_dwordx4 v142, s[52:53] offset:128
	s_waitcnt vmcnt(8)
	s_waitcnt lgkmcnt(0)
	s_barrier
	s_setprio 1
	s_waitcnt lgkmcnt(0)
	v_mfma_f32_16x16x32_bf16 v[62:65], v[130:133], v[172:175], v[62:65]
	v_mfma_f32_16x16x32_bf16 v[58:61], v[138:141], v[172:175], v[58:61]
	v_mfma_f32_16x16x32_bf16 v[54:57], v[130:133], v[180:183], v[54:57]
	v_mfma_f32_16x16x32_bf16 v[42:45], v[138:141], v[180:183], v[42:45]
	v_mfma_f32_16x16x32_bf16 v[38:41], v[130:133], v[204:207], v[38:41]
	v_mfma_f32_16x16x32_bf16 v[26:29], v[138:141], v[204:207], v[26:29]
	v_mfma_f32_16x16x32_bf16 v[22:25], v[130:133], v[212:215], v[22:25]
	v_mfma_f32_16x16x32_bf16 v[10:13], v[138:141], v[212:215], v[10:13]
	v_mfma_f32_16x16x32_bf16 v[62:65], v[134:137], v[176:179], v[62:65]
	v_mfma_f32_16x16x32_bf16 v[58:61], v[148:151], v[176:179], v[58:61]
	v_mfma_f32_16x16x32_bf16 v[54:57], v[134:137], v[200:203], v[54:57]
	v_mfma_f32_16x16x32_bf16 v[42:45], v[148:151], v[200:203], v[42:45]
	v_mfma_f32_16x16x32_bf16 v[38:41], v[134:137], v[208:211], v[38:41]
	v_mfma_f32_16x16x32_bf16 v[26:29], v[148:151], v[208:211], v[26:29]
	v_mfma_f32_16x16x32_bf16 v[22:25], v[134:137], v[216:219], v[22:25]
	v_mfma_f32_16x16x32_bf16 v[10:13], v[148:151], v[216:219], v[10:13]
	s_setprio 0
	s_setprio 1
	v_mfma_f32_16x16x32_bf16 v[50:53], v[152:155], v[172:175], v[50:53]
	v_mfma_f32_16x16x32_bf16 v[46:49], v[164:167], v[172:175], v[46:49]
	v_mfma_f32_16x16x32_bf16 v[34:37], v[152:155], v[180:183], v[34:37]
	v_mfma_f32_16x16x32_bf16 v[30:33], v[164:167], v[180:183], v[30:33]
	v_mfma_f32_16x16x32_bf16 v[18:21], v[152:155], v[204:207], v[18:21]
	v_mfma_f32_16x16x32_bf16 v[14:17], v[164:167], v[204:207], v[14:17]
	v_mfma_f32_16x16x32_bf16 v[6:9], v[152:155], v[212:215], v[6:9]
	v_mfma_f32_16x16x32_bf16 v[2:5], v[164:167], v[212:215], v[2:5]
	v_mfma_f32_16x16x32_bf16 v[50:53], v[160:163], v[176:179], v[50:53]
	v_mfma_f32_16x16x32_bf16 v[46:49], v[168:171], v[176:179], v[46:49]
	v_mfma_f32_16x16x32_bf16 v[34:37], v[160:163], v[200:203], v[34:37]
	v_mfma_f32_16x16x32_bf16 v[30:33], v[168:171], v[200:203], v[30:33]
	v_mfma_f32_16x16x32_bf16 v[18:21], v[160:163], v[208:211], v[18:21]
	v_mfma_f32_16x16x32_bf16 v[14:17], v[168:171], v[208:211], v[14:17]
	v_mfma_f32_16x16x32_bf16 v[6:9], v[160:163], v[216:219], v[6:9]
	v_mfma_f32_16x16x32_bf16 v[2:5], v[168:171], v[216:219], v[2:5]
	s_setprio 0
	s_barrier
	s_add_i32 s67, s67, 2
	s_add_u32 s65, s65, 0x100
	s_addc_u32 s66, s66, 0
	s_cmpk_gt_u32 s67, 0x7d
	s_mov_b64 s[46:47], s[48:49]
	s_cbranch_scc0 .LBB0_359
	s_and_b64 vcc, exec, s[12:13]
	s_cbranch_vccz .LBB0_362
	s_barrier
